# batched the serialized gate loads in the merge-GEMM epilogue, de-serialized conv loads and MoE gather-index loads
# speedup vs baseline: 1.0490x; 1.0490x over previous
.LBB0_125:
	s_add_i32 s35, 0, 0x10000
	v_add_u32_e32 v140, s35, v231
	ds_read_b128 v[128:131], v140
	ds_read_b128 v[132:135], v140 offset:1024
	ds_read_b128 v[136:139], v140 offset:2048
	ds_read_b128 v[140:143], v140 offset:3072
	s_add_u32 s14, s86, s10
	v_mov_b32_e32 v188, v228
	v_mov_b32_e32 v176, v229
	s_addc_u32 s15, s87, s11
	ds_read_b128 v[144:147], v233
	ds_read_b128 v[148:151], v233 offset:1024
	ds_read_b128 v[152:155], v233 offset:2048
	ds_read_b128 v[156:159], v233 offset:3072
	ds_read_b128 v[160:163], v233 offset:4096
	ds_read_b128 v[164:167], v233 offset:5120
	ds_read_b128 v[168:171], v233 offset:6144
	ds_read_b128 v[172:175], v233 offset:7168
	s_add_i32 s41, s22, 0xc000
	v_lshl_add_u64 v[178:179], s[14:15], 0, v[188:189]
	v_mov_b32_e32 v177, v189
	v_lshl_add_u64 v[178:179], v[178:179], 0, s[44:45]
	s_mov_b32 m0, s41
	v_lshl_add_u64 v[176:177], s[14:15], 0, v[176:177]
	s_add_i32 s42, s22, 0xe000
	global_load_lds_dwordx4 v[178:179], off
	v_lshl_add_u64 v[176:177], v[176:177], 0, s[44:45]
	s_mov_b32 m0, s42
	s_nop 0
	global_load_lds_dwordx4 v[176:177], off
	s_waitcnt lgkmcnt(8)
	s_barrier
	s_waitcnt lgkmcnt(0)
	s_setprio 1
	s_waitcnt lgkmcnt(0)
	v_mfma_f32_16x16x32_bf16 v[124:127], v[128:131], v[144:147], v[124:127]
	v_mfma_f32_16x16x32_bf16 v[120:123], v[136:139], v[144:147], v[120:123]
	v_mfma_f32_16x16x32_bf16 v[116:119], v[128:131], v[152:155], v[116:119]
	v_mfma_f32_16x16x32_bf16 v[112:115], v[136:139], v[152:155], v[112:115]
	v_mfma_f32_16x16x32_bf16 v[108:111], v[128:131], v[160:163], v[108:111]
	v_mfma_f32_16x16x32_bf16 v[104:107], v[136:139], v[160:163], v[104:107]
	v_mfma_f32_16x16x32_bf16 v[100:103], v[128:131], v[168:171], v[100:103]
	v_mfma_f32_16x16x32_bf16 v[96:99], v[136:139], v[168:171], v[96:99]
	v_mfma_f32_16x16x32_bf16 v[124:127], v[132:135], v[148:151], v[124:127]
	v_mfma_f32_16x16x32_bf16 v[120:123], v[140:143], v[148:151], v[120:123]
	v_mfma_f32_16x16x32_bf16 v[116:119], v[132:135], v[156:159], v[116:119]
	v_mfma_f32_16x16x32_bf16 v[112:115], v[140:143], v[156:159], v[112:115]
	v_mfma_f32_16x16x32_bf16 v[108:111], v[132:135], v[164:167], v[108:111]
	v_mfma_f32_16x16x32_bf16 v[104:107], v[140:143], v[164:167], v[104:107]
	v_mfma_f32_16x16x32_bf16 v[100:103], v[132:135], v[172:175], v[100:103]
	v_mfma_f32_16x16x32_bf16 v[96:99], v[140:143], v[172:175], v[96:99]
	s_setprio 0
	s_barrier
	s_add_i32 s36, 0, 0x14000
	s_add_u32 s16, s12, s10
	v_add_u32_e32 v234, s36, v231
	v_mov_b32_e32 v188, v224
	v_mov_b32_e32 v194, v225
	s_addc_u32 s17, s13, s11
	ds_read_b128 v[176:179], v234
	ds_read_b128 v[180:183], v234 offset:1024
	ds_read_b128 v[184:187], v234 offset:2048
	ds_read_b128 v[190:193], v234 offset:3072
	s_add_i32 s35, s35, s21
	v_lshl_add_u64 v[196:197], s[16:17], 0, v[188:189]
	v_mov_b32_e32 v195, v189
	v_lshl_add_u64 v[196:197], v[196:197], 0, s[88:89]
	s_mov_b32 m0, s35
	v_lshl_add_u64 v[194:195], s[16:17], 0, v[194:195]
	global_load_lds_dwordx4 v[196:197], off
	v_lshl_add_u64 v[194:195], v[194:195], 0, s[88:89]
	s_add_i32 m0, s35, 0x2000
	s_nop 0
	global_load_lds_dwordx4 v[194:195], off
	s_barrier
	s_waitcnt lgkmcnt(0)
	s_setprio 1
	s_waitcnt lgkmcnt(0)
	v_mfma_f32_16x16x32_bf16 v[92:95], v[176:179], v[144:147], v[92:95]
	v_mfma_f32_16x16x32_bf16 v[88:91], v[184:187], v[144:147], v[88:91]
	v_mfma_f32_16x16x32_bf16 v[84:87], v[176:179], v[152:155], v[84:87]
	v_mfma_f32_16x16x32_bf16 v[80:83], v[184:187], v[152:155], v[80:83]
	v_mfma_f32_16x16x32_bf16 v[76:79], v[176:179], v[160:163], v[76:79]
	v_mfma_f32_16x16x32_bf16 v[72:75], v[184:187], v[160:163], v[72:75]
	v_mfma_f32_16x16x32_bf16 v[68:71], v[176:179], v[168:171], v[68:71]
	v_mfma_f32_16x16x32_bf16 v[64:67], v[184:187], v[168:171], v[64:67]
	v_mfma_f32_16x16x32_bf16 v[92:95], v[180:183], v[148:151], v[92:95]
	v_mfma_f32_16x16x32_bf16 v[88:91], v[190:193], v[148:151], v[88:91]
	v_mfma_f32_16x16x32_bf16 v[84:87], v[180:183], v[156:159], v[84:87]
	v_mfma_f32_16x16x32_bf16 v[80:83], v[190:193], v[156:159], v[80:83]
	v_mfma_f32_16x16x32_bf16 v[76:79], v[180:183], v[164:167], v[76:79]
	v_mfma_f32_16x16x32_bf16 v[72:75], v[190:193], v[164:167], v[72:75]
	v_mfma_f32_16x16x32_bf16 v[68:71], v[180:183], v[172:175], v[68:71]
	v_mfma_f32_16x16x32_bf16 v[64:67], v[190:193], v[172:175], v[64:67]
	s_setprio 0
	v_mov_b32_e32 v188, v226
	v_mov_b32_e32 v194, v227
	s_barrier
	ds_read_b128 v[144:147], v233 offset:16384
	ds_read_b128 v[148:151], v233 offset:17408
	ds_read_b128 v[152:155], v233 offset:18432
	ds_read_b128 v[156:159], v233 offset:19456
	ds_read_b128 v[160:163], v233 offset:20480
	ds_read_b128 v[164:167], v233 offset:21504
	ds_read_b128 v[168:171], v233 offset:22528
	ds_read_b128 v[172:175], v233 offset:23552
	v_mov_b32_e32 v195, v189
	v_lshl_add_u64 v[196:197], s[14:15], 0, v[188:189]
	s_mov_b32 m0, s22
	v_lshl_add_u64 v[196:197], v[196:197], 0, s[46:47]
	v_lshl_add_u64 v[194:195], s[14:15], 0, v[194:195]
	global_load_lds_dwordx4 v[196:197], off
	v_lshl_add_u64 v[194:195], v[194:195], 0, s[46:47]
	s_mov_b32 m0, s25
	s_nop 0
	global_load_lds_dwordx4 v[194:195], off
	s_barrier
	s_waitcnt lgkmcnt(0)
	s_setprio 1
	s_waitcnt lgkmcnt(0)
	v_mfma_f32_16x16x32_bf16 v[60:63], v[128:131], v[144:147], v[60:63]
	v_mfma_f32_16x16x32_bf16 v[56:59], v[136:139], v[144:147], v[56:59]
	v_mfma_f32_16x16x32_bf16 v[52:55], v[128:131], v[152:155], v[52:55]
	v_mfma_f32_16x16x32_bf16 v[48:51], v[136:139], v[152:155], v[48:51]
	v_mfma_f32_16x16x32_bf16 v[44:47], v[128:131], v[160:163], v[44:47]
	v_mfma_f32_16x16x32_bf16 v[40:43], v[136:139], v[160:163], v[40:43]
	v_mfma_f32_16x16x32_bf16 v[36:39], v[128:131], v[168:171], v[36:39]
	v_mfma_f32_16x16x32_bf16 v[32:35], v[136:139], v[168:171], v[32:35]
	v_mfma_f32_16x16x32_bf16 v[60:63], v[132:135], v[148:151], v[60:63]
	v_mfma_f32_16x16x32_bf16 v[56:59], v[140:143], v[148:151], v[56:59]
	v_mfma_f32_16x16x32_bf16 v[52:55], v[132:135], v[156:159], v[52:55]
	v_mfma_f32_16x16x32_bf16 v[48:51], v[140:143], v[156:159], v[48:51]
	v_mfma_f32_16x16x32_bf16 v[44:47], v[132:135], v[164:167], v[44:47]
	v_mfma_f32_16x16x32_bf16 v[40:43], v[140:143], v[164:167], v[40:43]
	v_mfma_f32_16x16x32_bf16 v[36:39], v[132:135], v[172:175], v[36:39]
	v_mfma_f32_16x16x32_bf16 v[32:35], v[140:143], v[172:175], v[32:35]
	s_setprio 0
	s_barrier
	v_mov_b32_e32 v188, v224
	v_mov_b32_e32 v128, v225
	s_add_i32 s35, s36, s21
	v_lshl_add_u64 v[130:131], s[16:17], 0, v[188:189]
	v_mov_b32_e32 v129, v189
	v_lshl_add_u64 v[130:131], v[130:131], 0, s[48:49]
	s_mov_b32 m0, s35
	v_lshl_add_u64 v[128:129], s[16:17], 0, v[128:129]
	s_add_i32 s36, s35, 0x2000
	global_load_lds_dwordx4 v[130:131], off
	v_lshl_add_u64 v[128:129], v[128:129], 0, s[48:49]
	s_mov_b32 m0, s36
	s_nop 0
	global_load_lds_dwordx4 v[128:129], off
	s_waitcnt vmcnt(6)
	s_barrier
	s_setprio 1
	v_mfma_f32_16x16x32_bf16 v[28:31], v[176:179], v[144:147], v[28:31]
	v_mfma_f32_16x16x32_bf16 v[24:27], v[184:187], v[144:147], v[24:27]
	v_mfma_f32_16x16x32_bf16 v[20:23], v[176:179], v[152:155], v[20:23]
	v_mfma_f32_16x16x32_bf16 v[16:19], v[184:187], v[152:155], v[16:19]
	v_mfma_f32_16x16x32_bf16 v[12:15], v[176:179], v[160:163], v[12:15]
	v_mfma_f32_16x16x32_bf16 v[8:11], v[184:187], v[160:163], v[8:11]
	v_mfma_f32_16x16x32_bf16 v[4:7], v[176:179], v[168:171], v[4:7]
	v_mfma_f32_16x16x32_bf16 v[0:3], v[184:187], v[168:171], v[0:3]
	v_mfma_f32_16x16x32_bf16 v[28:31], v[180:183], v[148:151], v[28:31]
	v_mfma_f32_16x16x32_bf16 v[24:27], v[190:193], v[148:151], v[24:27]
	v_mfma_f32_16x16x32_bf16 v[20:23], v[180:183], v[156:159], v[20:23]
	v_mfma_f32_16x16x32_bf16 v[16:19], v[190:193], v[156:159], v[16:19]
	v_mfma_f32_16x16x32_bf16 v[12:15], v[180:183], v[164:167], v[12:15]
	v_mfma_f32_16x16x32_bf16 v[8:11], v[190:193], v[164:167], v[8:11]
	v_mfma_f32_16x16x32_bf16 v[4:7], v[180:183], v[172:175], v[4:7]
	v_mfma_f32_16x16x32_bf16 v[0:3], v[190:193], v[172:175], v[0:3]
	s_setprio 0
	s_add_i32 s40, 0, 0x18000
	v_add_u32_e32 v235, s40, v231
	s_barrier
	ds_read_b128 v[128:131], v235
	ds_read_b128 v[132:135], v235 offset:1024
	ds_read_b128 v[136:139], v235 offset:2048
	ds_read_b128 v[140:143], v235 offset:3072
	v_mov_b32_e32 v188, v228
	v_mov_b32_e32 v176, v229
	ds_read_b128 v[144:147], v233 offset:32768
	ds_read_b128 v[148:151], v233 offset:33792
	ds_read_b128 v[152:155], v233 offset:34816
	ds_read_b128 v[156:159], v233 offset:35840
	ds_read_b128 v[160:163], v233 offset:36864
	ds_read_b128 v[164:167], v233 offset:37888
	ds_read_b128 v[168:171], v233 offset:38912
	ds_read_b128 v[172:175], v233 offset:39936
	v_mov_b32_e32 v177, v189
	v_lshl_add_u64 v[178:179], s[14:15], 0, v[188:189]
	s_mov_b32 m0, s26
	v_lshl_add_u64 v[178:179], v[178:179], 0, s[46:47]
	v_lshl_add_u64 v[176:177], s[14:15], 0, v[176:177]
	global_load_lds_dwordx4 v[178:179], off
	v_lshl_add_u64 v[176:177], v[176:177], 0, s[46:47]
	s_mov_b32 m0, s27
	s_nop 0
	global_load_lds_dwordx4 v[176:177], off
	s_waitcnt lgkmcnt(8)
	s_barrier
	s_waitcnt lgkmcnt(0)
	s_setprio 1
	s_waitcnt lgkmcnt(0)
	v_mfma_f32_16x16x32_bf16 v[124:127], v[128:131], v[144:147], v[124:127]
	v_mfma_f32_16x16x32_bf16 v[120:123], v[136:139], v[144:147], v[120:123]
	v_mfma_f32_16x16x32_bf16 v[116:119], v[128:131], v[152:155], v[116:119]
	v_mfma_f32_16x16x32_bf16 v[112:115], v[136:139], v[152:155], v[112:115]
	v_mfma_f32_16x16x32_bf16 v[108:111], v[128:131], v[160:163], v[108:111]
	v_mfma_f32_16x16x32_bf16 v[104:107], v[136:139], v[160:163], v[104:107]
	v_mfma_f32_16x16x32_bf16 v[100:103], v[128:131], v[168:171], v[100:103]
	v_mfma_f32_16x16x32_bf16 v[96:99], v[136:139], v[168:171], v[96:99]
	v_mfma_f32_16x16x32_bf16 v[124:127], v[132:135], v[148:151], v[124:127]
	v_mfma_f32_16x16x32_bf16 v[120:123], v[140:143], v[148:151], v[120:123]
	v_mfma_f32_16x16x32_bf16 v[116:119], v[132:135], v[156:159], v[116:119]
	v_mfma_f32_16x16x32_bf16 v[112:115], v[140:143], v[156:159], v[112:115]
	v_mfma_f32_16x16x32_bf16 v[108:111], v[132:135], v[164:167], v[108:111]
	v_mfma_f32_16x16x32_bf16 v[104:107], v[140:143], v[164:167], v[104:107]
	v_mfma_f32_16x16x32_bf16 v[100:103], v[132:135], v[172:175], v[100:103]
	v_mfma_f32_16x16x32_bf16 v[96:99], v[140:143], v[172:175], v[96:99]
	s_setprio 0
	s_barrier
	s_add_i32 s43, 0, 0x1c000
	v_add_u32_e32 v236, s43, v231
	v_mov_b32_e32 v188, v224
	v_mov_b32_e32 v194, v225
	ds_read_b128 v[176:179], v236
	ds_read_b128 v[180:183], v236 offset:1024
	ds_read_b128 v[184:187], v236 offset:2048
	ds_read_b128 v[190:193], v236 offset:3072
	s_add_i32 s40, s40, s21
	v_lshl_add_u64 v[196:197], s[16:17], 0, v[188:189]
	v_mov_b32_e32 v195, v189
	v_lshl_add_u64 v[196:197], v[196:197], 0, s[2:3]
	s_mov_b32 m0, s40
	v_lshl_add_u64 v[194:195], s[16:17], 0, v[194:195]
	s_add_i32 s37, s40, 0x2000
	global_load_lds_dwordx4 v[196:197], off
	v_lshl_add_u64 v[194:195], v[194:195], 0, s[2:3]
	s_mov_b32 m0, s37
	s_nop 0
	global_load_lds_dwordx4 v[194:195], off
	s_barrier
	s_waitcnt lgkmcnt(0)
	s_setprio 1
	s_waitcnt lgkmcnt(0)
	v_mfma_f32_16x16x32_bf16 v[92:95], v[176:179], v[144:147], v[92:95]
	v_mfma_f32_16x16x32_bf16 v[88:91], v[184:187], v[144:147], v[88:91]
	v_mfma_f32_16x16x32_bf16 v[84:87], v[176:179], v[152:155], v[84:87]
	v_mfma_f32_16x16x32_bf16 v[80:83], v[184:187], v[152:155], v[80:83]
	v_mfma_f32_16x16x32_bf16 v[76:79], v[176:179], v[160:163], v[76:79]
	v_mfma_f32_16x16x32_bf16 v[72:75], v[184:187], v[160:163], v[72:75]
	v_mfma_f32_16x16x32_bf16 v[68:71], v[176:179], v[168:171], v[68:71]
	v_mfma_f32_16x16x32_bf16 v[64:67], v[184:187], v[168:171], v[64:67]
	v_mfma_f32_16x16x32_bf16 v[92:95], v[180:183], v[148:151], v[92:95]
	v_mfma_f32_16x16x32_bf16 v[88:91], v[190:193], v[148:151], v[88:91]
	v_mfma_f32_16x16x32_bf16 v[84:87], v[180:183], v[156:159], v[84:87]
	v_mfma_f32_16x16x32_bf16 v[80:83], v[190:193], v[156:159], v[80:83]
	v_mfma_f32_16x16x32_bf16 v[76:79], v[180:183], v[164:167], v[76:79]
	v_mfma_f32_16x16x32_bf16 v[72:75], v[190:193], v[164:167], v[72:75]
	v_mfma_f32_16x16x32_bf16 v[68:71], v[180:183], v[172:175], v[68:71]
	v_mfma_f32_16x16x32_bf16 v[64:67], v[190:193], v[172:175], v[64:67]
	s_setprio 0
	v_mov_b32_e32 v188, v226
	v_mov_b32_e32 v194, v227
	s_barrier
	ds_read_b128 v[144:147], v233 offset:49152
	ds_read_b128 v[148:151], v233 offset:50176
	ds_read_b128 v[152:155], v233 offset:51200
	ds_read_b128 v[156:159], v233 offset:52224
	ds_read_b128 v[160:163], v233 offset:53248
	ds_read_b128 v[164:167], v233 offset:54272
	ds_read_b128 v[168:171], v233 offset:55296
	ds_read_b128 v[172:175], v233 offset:56320
	v_mov_b32_e32 v195, v189
	v_lshl_add_u64 v[196:197], s[14:15], 0, v[188:189]
	s_mov_b32 m0, s28
	v_lshl_add_u64 v[196:197], v[196:197], 0, s[50:51]
	v_lshl_add_u64 v[194:195], s[14:15], 0, v[194:195]
	global_load_lds_dwordx4 v[196:197], off
	v_lshl_add_u64 v[194:195], v[194:195], 0, s[50:51]
	s_mov_b32 m0, s29
	s_nop 0
	global_load_lds_dwordx4 v[194:195], off
	s_barrier
	s_waitcnt lgkmcnt(0)
	s_setprio 1
	s_waitcnt lgkmcnt(0)
	v_mfma_f32_16x16x32_bf16 v[60:63], v[128:131], v[144:147], v[60:63]
	v_mfma_f32_16x16x32_bf16 v[56:59], v[136:139], v[144:147], v[56:59]
	v_mfma_f32_16x16x32_bf16 v[52:55], v[128:131], v[152:155], v[52:55]
	v_mfma_f32_16x16x32_bf16 v[48:51], v[136:139], v[152:155], v[48:51]
	v_mfma_f32_16x16x32_bf16 v[44:47], v[128:131], v[160:163], v[44:47]
	v_mfma_f32_16x16x32_bf16 v[40:43], v[136:139], v[160:163], v[40:43]
	v_mfma_f32_16x16x32_bf16 v[36:39], v[128:131], v[168:171], v[36:39]
	v_mfma_f32_16x16x32_bf16 v[32:35], v[136:139], v[168:171], v[32:35]
	v_mfma_f32_16x16x32_bf16 v[60:63], v[132:135], v[148:151], v[60:63]
	v_mfma_f32_16x16x32_bf16 v[56:59], v[140:143], v[148:151], v[56:59]
	v_mfma_f32_16x16x32_bf16 v[52:55], v[132:135], v[156:159], v[52:55]
	v_mfma_f32_16x16x32_bf16 v[48:51], v[140:143], v[156:159], v[48:51]
	v_mfma_f32_16x16x32_bf16 v[44:47], v[132:135], v[164:167], v[44:47]
	v_mfma_f32_16x16x32_bf16 v[40:43], v[140:143], v[164:167], v[40:43]
	v_mfma_f32_16x16x32_bf16 v[36:39], v[132:135], v[172:175], v[36:39]
	v_mfma_f32_16x16x32_bf16 v[32:35], v[140:143], v[172:175], v[32:35]
	s_setprio 0
	s_barrier
	v_mov_b32_e32 v188, v224
	v_mov_b32_e32 v128, v225
	s_add_i32 s14, s43, s21
	v_lshl_add_u64 v[130:131], s[16:17], 0, v[188:189]
	v_mov_b32_e32 v129, v189
	v_lshl_add_u64 v[130:131], v[130:131], 0, s[52:53]
	s_mov_b32 m0, s14
	v_lshl_add_u64 v[128:129], s[16:17], 0, v[128:129]
	s_add_i32 s15, s14, 0x2000
	global_load_lds_dwordx4 v[130:131], off
	v_lshl_add_u64 v[128:129], v[128:129], 0, s[52:53]
	s_mov_b32 m0, s15
	s_nop 0
	global_load_lds_dwordx4 v[128:129], off
	s_waitcnt vmcnt(6)
	s_barrier
	s_setprio 1
	v_mfma_f32_16x16x32_bf16 v[28:31], v[176:179], v[144:147], v[28:31]
	v_mfma_f32_16x16x32_bf16 v[24:27], v[184:187], v[144:147], v[24:27]
	v_mfma_f32_16x16x32_bf16 v[20:23], v[176:179], v[152:155], v[20:23]
	v_mfma_f32_16x16x32_bf16 v[16:19], v[184:187], v[152:155], v[16:19]
	v_mfma_f32_16x16x32_bf16 v[12:15], v[176:179], v[160:163], v[12:15]
	v_mfma_f32_16x16x32_bf16 v[8:11], v[184:187], v[160:163], v[8:11]
	v_mfma_f32_16x16x32_bf16 v[4:7], v[176:179], v[168:171], v[4:7]
	v_mfma_f32_16x16x32_bf16 v[0:3], v[184:187], v[168:171], v[0:3]
	v_mfma_f32_16x16x32_bf16 v[28:31], v[180:183], v[148:151], v[28:31]
	v_mfma_f32_16x16x32_bf16 v[24:27], v[190:193], v[148:151], v[24:27]
	v_mfma_f32_16x16x32_bf16 v[20:23], v[180:183], v[156:159], v[20:23]
	v_mfma_f32_16x16x32_bf16 v[16:19], v[190:193], v[156:159], v[16:19]
	v_mfma_f32_16x16x32_bf16 v[12:15], v[180:183], v[164:167], v[12:15]
	v_mfma_f32_16x16x32_bf16 v[8:11], v[190:193], v[164:167], v[8:11]
	v_mfma_f32_16x16x32_bf16 v[4:7], v[180:183], v[172:175], v[4:7]
	v_mfma_f32_16x16x32_bf16 v[0:3], v[190:193], v[172:175], v[0:3]
	s_setprio 0
	s_add_i32 s9, s9, 2
	s_add_u32 s10, s10, 0x100
	s_addc_u32 s11, s11, 0
	s_cmp_lt_u32 s9, 12
	s_barrier
	s_cbranch_scc1 .LBB0_125
	v_add_u32_e32 v128, 0, v231
	v_add_u32_e32 v128, 0x10000, v128
	ds_read_b128 v[140:143], v128
	ds_read_b128 v[144:147], v128 offset:1024
	ds_read_b128 v[148:151], v128 offset:2048
	ds_read_b128 v[152:155], v128 offset:3072
	v_readlane_b32 s10, v252, 14
	v_mov_b32_e32 v128, v228
	v_mov_b32_e32 v129, v229
	s_mov_b32 m0, s41
	v_readlane_b32 s11, v252, 15
	ds_read_b128 v[180:183], v233
	ds_read_b128 v[184:187], v233 offset:1024
	ds_read_b128 v[172:175], v233 offset:2048
	ds_read_b128 v[176:179], v233 offset:3072
	ds_read_b128 v[164:167], v233 offset:4096
	ds_read_b128 v[168:171], v233 offset:5120
	ds_read_b128 v[156:159], v233 offset:6144
	ds_read_b128 v[160:163], v233 offset:7168
	s_nop 0
	global_load_lds_dwordx4 v128, s[10:11]
	s_mov_b32 m0, s42
	s_nop 0
	global_load_lds_dwordx4 v129, s[10:11]
	s_waitcnt lgkmcnt(8)
	s_barrier
	s_waitcnt lgkmcnt(0)
	s_setprio 1
	s_waitcnt lgkmcnt(0)
	v_mfma_f32_16x16x32_bf16 v[124:127], v[140:143], v[180:183], v[124:127]
	v_mfma_f32_16x16x32_bf16 v[120:123], v[148:151], v[180:183], v[120:123]
	v_mfma_f32_16x16x32_bf16 v[116:119], v[140:143], v[172:175], v[116:119]
	v_mfma_f32_16x16x32_bf16 v[112:115], v[148:151], v[172:175], v[112:115]
	v_mfma_f32_16x16x32_bf16 v[108:111], v[140:143], v[164:167], v[108:111]
	v_mfma_f32_16x16x32_bf16 v[104:107], v[148:151], v[164:167], v[104:107]
	v_mfma_f32_16x16x32_bf16 v[100:103], v[140:143], v[156:159], v[100:103]
	v_mfma_f32_16x16x32_bf16 v[96:99], v[148:151], v[156:159], v[96:99]
	v_mfma_f32_16x16x32_bf16 v[124:127], v[144:147], v[184:187], v[124:127]
	v_mfma_f32_16x16x32_bf16 v[120:123], v[152:155], v[184:187], v[120:123]
	v_mfma_f32_16x16x32_bf16 v[116:119], v[144:147], v[176:179], v[116:119]
	v_mfma_f32_16x16x32_bf16 v[128:131], v[152:155], v[176:179], v[112:115]
	v_mfma_f32_16x16x32_bf16 v[108:111], v[144:147], v[168:171], v[108:111]
	v_mfma_f32_16x16x32_bf16 v[132:135], v[152:155], v[168:171], v[104:107]
	v_mfma_f32_16x16x32_bf16 v[100:103], v[144:147], v[160:163], v[100:103]
	v_mfma_f32_16x16x32_bf16 v[136:139], v[152:155], v[160:163], v[96:99]
	s_setprio 0
	s_barrier
	s_andn2_b64 vcc, exec, s[6:7]
	s_cbranch_vccnz .LBB0_117
	v_lshl_add_u32 v96, s31, 8, v222
	v_readlane_b32 s10, v252, 26
	v_ashrrev_i32_e32 v97, 31, v96
	v_readlane_b32 s11, v252, 27
	s_nop 1
	v_lshl_add_u64 v[98:99], v[96:97], 2, s[10:11]
	global_load_dword v198, v[98:99], off
	global_load_dword v199, v[98:99], off offset:256
	global_load_dword v200, v[98:99], off offset:512
	global_load_dword v201, v[98:99], off offset:768
	s_waitcnt vmcnt(0)
	v_lshl_add_u32 v226, v198, 11, v223
	v_lshl_add_u32 v227, v199, 11, v223
	v_lshl_add_u32 v228, v200, 11, v223
	v_lshl_add_u32 v229, v201, 11, v223
	s_branch .LBB0_117

.LBB0_357:
	s_add_i32 s43, 0, 0x10000
	v_add_u32_e32 v128, s43, v151
	ds_read_b128 v[130:133], v128
	ds_read_b128 v[138:141], v128 offset:1024
	ds_read_b128 v[142:145], v128 offset:2048
	ds_read_b128 v[154:157], v128 offset:3072
	s_add_u32 s22, s10, s6
	v_mov_b32_e32 v188, v146
	v_mov_b32_e32 v134, v148
	s_addc_u32 s23, s11, s7
	ds_read_b128 v[158:161], v153
	ds_read_b128 v[162:165], v153 offset:1024
	ds_read_b128 v[166:169], v153 offset:2048
	ds_read_b128 v[170:173], v153 offset:3072
	ds_read_b128 v[174:177], v153 offset:4096
	ds_read_b128 v[178:181], v153 offset:5120
	ds_read_b128 v[182:185], v153 offset:6144
	ds_read_b128 v[190:193], v153 offset:7168
	s_add_i32 s15, s30, 0xc000
	v_lshl_add_u64 v[186:187], s[22:23], 0, v[188:189]
	v_mov_b32_e32 v135, v189
	v_lshl_add_u64 v[186:187], v[186:187], 0, s[50:51]
	s_mov_b32 m0, s15
	v_lshl_add_u64 v[134:135], s[22:23], 0, v[134:135]
	s_add_i32 s17, s30, 0xe000
	global_load_lds_dwordx4 v[186:187], off
	v_lshl_add_u64 v[134:135], v[134:135], 0, s[50:51]
	s_mov_b32 m0, s17
	s_nop 0
	global_load_lds_dwordx4 v[134:135], off
	s_waitcnt lgkmcnt(8)
	s_barrier
	s_waitcnt lgkmcnt(0)
	s_setprio 1
	s_waitcnt lgkmcnt(0)
	v_mfma_f32_16x16x32_bf16 v[4:7], v[130:133], v[158:161], v[4:7]
	v_mfma_f32_16x16x32_bf16 v[0:3], v[142:145], v[158:161], v[0:3]
	v_mfma_f32_16x16x32_bf16 v[20:23], v[130:133], v[166:169], v[20:23]
	v_mfma_f32_16x16x32_bf16 v[16:19], v[142:145], v[166:169], v[16:19]
	v_mfma_f32_16x16x32_bf16 v[36:39], v[130:133], v[174:177], v[36:39]
	v_mfma_f32_16x16x32_bf16 v[32:35], v[142:145], v[174:177], v[32:35]
	v_mfma_f32_16x16x32_bf16 v[52:55], v[130:133], v[182:185], v[52:55]
	v_mfma_f32_16x16x32_bf16 v[48:51], v[142:145], v[182:185], v[48:51]
	v_mfma_f32_16x16x32_bf16 v[4:7], v[138:141], v[162:165], v[4:7]
	v_mfma_f32_16x16x32_bf16 v[0:3], v[154:157], v[162:165], v[0:3]
	v_mfma_f32_16x16x32_bf16 v[20:23], v[138:141], v[170:173], v[20:23]
	v_mfma_f32_16x16x32_bf16 v[16:19], v[154:157], v[170:173], v[16:19]
	v_mfma_f32_16x16x32_bf16 v[36:39], v[138:141], v[178:181], v[36:39]
	v_mfma_f32_16x16x32_bf16 v[32:35], v[154:157], v[178:181], v[32:35]
	v_mfma_f32_16x16x32_bf16 v[52:55], v[138:141], v[190:193], v[52:55]
	v_mfma_f32_16x16x32_bf16 v[48:51], v[154:157], v[190:193], v[48:51]
	s_setprio 0
	s_barrier
	s_add_i32 s45, 0, 0x14000
	s_add_u32 s24, s8, s6
	v_add_u32_e32 v129, s45, v151
	v_mov_b32_e32 v188, v147
	v_mov_b32_e32 v134, v149
	s_addc_u32 s25, s9, s7
	ds_read_b128 v[202:205], v129
	ds_read_b128 v[222:225], v129 offset:1024
	ds_read_b128 v[226:229], v129 offset:2048
	ds_read_b128 v[230:233], v129 offset:3072
	s_add_i32 s43, s43, s29
	v_lshl_add_u64 v[186:187], s[24:25], 0, v[188:189]
	v_mov_b32_e32 v135, v189
	v_lshl_add_u64 v[186:187], v[186:187], 0, s[88:89]
	s_mov_b32 m0, s43
	v_lshl_add_u64 v[134:135], s[24:25], 0, v[134:135]
	s_add_i32 s44, s43, 0x2000
	global_load_lds_dwordx4 v[186:187], off
	v_lshl_add_u64 v[134:135], v[134:135], 0, s[88:89]
	s_mov_b32 m0, s44
	s_nop 0
	global_load_lds_dwordx4 v[134:135], off
	s_barrier
	s_waitcnt lgkmcnt(0)
	s_setprio 1
	s_waitcnt lgkmcnt(0)
	v_mfma_f32_16x16x32_bf16 v[12:15], v[202:205], v[158:161], v[12:15]
	v_mfma_f32_16x16x32_bf16 v[8:11], v[226:229], v[158:161], v[8:11]
	v_mfma_f32_16x16x32_bf16 v[28:31], v[202:205], v[166:169], v[28:31]
	v_mfma_f32_16x16x32_bf16 v[24:27], v[226:229], v[166:169], v[24:27]
	v_mfma_f32_16x16x32_bf16 v[44:47], v[202:205], v[174:177], v[44:47]
	v_mfma_f32_16x16x32_bf16 v[40:43], v[226:229], v[174:177], v[40:43]
	v_mfma_f32_16x16x32_bf16 v[60:63], v[202:205], v[182:185], v[60:63]
	v_mfma_f32_16x16x32_bf16 v[56:59], v[226:229], v[182:185], v[56:59]
	v_mfma_f32_16x16x32_bf16 v[12:15], v[222:225], v[162:165], v[12:15]
	v_mfma_f32_16x16x32_bf16 v[8:11], v[230:233], v[162:165], v[8:11]
	v_mfma_f32_16x16x32_bf16 v[28:31], v[222:225], v[170:173], v[28:31]
	v_mfma_f32_16x16x32_bf16 v[24:27], v[230:233], v[170:173], v[24:27]
	v_mfma_f32_16x16x32_bf16 v[44:47], v[222:225], v[178:181], v[44:47]
	v_mfma_f32_16x16x32_bf16 v[40:43], v[230:233], v[178:181], v[40:43]
	v_mfma_f32_16x16x32_bf16 v[60:63], v[222:225], v[190:193], v[60:63]
	v_mfma_f32_16x16x32_bf16 v[56:59], v[230:233], v[190:193], v[56:59]
	s_setprio 0
	v_mov_b32_e32 v188, v146
	v_mov_b32_e32 v134, v148
	s_barrier
	ds_read_b128 v[158:161], v153 offset:16384
	ds_read_b128 v[162:165], v153 offset:17408
	ds_read_b128 v[166:169], v153 offset:18432
	ds_read_b128 v[170:173], v153 offset:19456
	ds_read_b128 v[174:177], v153 offset:20480
	ds_read_b128 v[178:181], v153 offset:21504
	ds_read_b128 v[182:185], v153 offset:22528
	ds_read_b128 v[190:193], v153 offset:23552
	v_mov_b32_e32 v135, v189
	v_lshl_add_u64 v[186:187], s[22:23], 0, v[188:189]
	s_mov_b32 m0, s30
	v_lshl_add_u64 v[186:187], v[186:187], 0, s[88:89]
	v_lshl_add_u64 v[134:135], s[22:23], 0, v[134:135]
	global_load_lds_dwordx4 v[186:187], off
	v_lshl_add_u64 v[134:135], v[134:135], 0, s[88:89]
	s_mov_b32 m0, s31
	s_nop 0
	global_load_lds_dwordx4 v[134:135], off
	s_barrier
	s_waitcnt lgkmcnt(0)
	s_setprio 1
	s_waitcnt lgkmcnt(0)
	v_mfma_f32_16x16x32_bf16 v[68:71], v[130:133], v[158:161], v[68:71]
	v_mfma_f32_16x16x32_bf16 v[64:67], v[142:145], v[158:161], v[64:67]
	v_mfma_f32_16x16x32_bf16 v[84:87], v[130:133], v[166:169], v[84:87]
	v_mfma_f32_16x16x32_bf16 v[80:83], v[142:145], v[166:169], v[80:83]
	v_mfma_f32_16x16x32_bf16 v[100:103], v[130:133], v[174:177], v[100:103]
	v_mfma_f32_16x16x32_bf16 v[96:99], v[142:145], v[174:177], v[96:99]
	v_mfma_f32_16x16x32_bf16 v[120:123], v[130:133], v[182:185], v[120:123]
	v_mfma_f32_16x16x32_bf16 v[116:119], v[142:145], v[182:185], v[116:119]
	v_mfma_f32_16x16x32_bf16 v[68:71], v[138:141], v[162:165], v[68:71]
	v_mfma_f32_16x16x32_bf16 v[64:67], v[154:157], v[162:165], v[64:67]
	v_mfma_f32_16x16x32_bf16 v[84:87], v[138:141], v[170:173], v[84:87]
	v_mfma_f32_16x16x32_bf16 v[80:83], v[154:157], v[170:173], v[80:83]
	v_mfma_f32_16x16x32_bf16 v[100:103], v[138:141], v[178:181], v[100:103]
	v_mfma_f32_16x16x32_bf16 v[96:99], v[154:157], v[178:181], v[96:99]
	v_mfma_f32_16x16x32_bf16 v[120:123], v[138:141], v[190:193], v[120:123]
	v_mfma_f32_16x16x32_bf16 v[116:119], v[154:157], v[190:193], v[116:119]
	s_setprio 0
	s_barrier
	v_mov_b32_e32 v188, v147
	v_mov_b32_e32 v130, v149
	s_add_i32 s45, s45, s29
	v_lshl_add_u64 v[132:133], s[24:25], 0, v[188:189]
	v_mov_b32_e32 v131, v189
	v_lshl_add_u64 v[132:133], v[132:133], 0, s[52:53]
	s_mov_b32 m0, s45
	v_lshl_add_u64 v[130:131], s[24:25], 0, v[130:131]
	s_add_i32 s46, s45, 0x2000
	global_load_lds_dwordx4 v[132:133], off
	v_lshl_add_u64 v[130:131], v[130:131], 0, s[52:53]
	s_mov_b32 m0, s46
	s_nop 0
	global_load_lds_dwordx4 v[130:131], off
	s_waitcnt vmcnt(6)
	s_barrier
	s_setprio 1
	v_mfma_f32_16x16x32_bf16 v[76:79], v[202:205], v[158:161], v[76:79]
	v_mfma_f32_16x16x32_bf16 v[72:75], v[226:229], v[158:161], v[72:75]
	v_mfma_f32_16x16x32_bf16 v[92:95], v[202:205], v[166:169], v[92:95]
	v_mfma_f32_16x16x32_bf16 v[88:91], v[226:229], v[166:169], v[88:91]
	v_mfma_f32_16x16x32_bf16 v[108:111], v[202:205], v[174:177], v[108:111]
	v_mfma_f32_16x16x32_bf16 v[104:107], v[226:229], v[174:177], v[104:107]
	v_mfma_f32_16x16x32_bf16 v[124:127], v[202:205], v[182:185], v[124:127]
	v_mfma_f32_16x16x32_bf16 v[112:115], v[226:229], v[182:185], v[112:115]
	v_mfma_f32_16x16x32_bf16 v[76:79], v[222:225], v[162:165], v[76:79]
	v_mfma_f32_16x16x32_bf16 v[72:75], v[230:233], v[162:165], v[72:75]
	v_mfma_f32_16x16x32_bf16 v[92:95], v[222:225], v[170:173], v[92:95]
	v_mfma_f32_16x16x32_bf16 v[88:91], v[230:233], v[170:173], v[88:91]
	v_mfma_f32_16x16x32_bf16 v[108:111], v[222:225], v[178:181], v[108:111]
	v_mfma_f32_16x16x32_bf16 v[104:107], v[230:233], v[178:181], v[104:107]
	v_mfma_f32_16x16x32_bf16 v[124:127], v[222:225], v[190:193], v[124:127]
	v_mfma_f32_16x16x32_bf16 v[112:115], v[230:233], v[190:193], v[112:115]
	s_setprio 0
	s_add_i32 s48, 0, 0x18000
	v_add_u32_e32 v130, s48, v151
	s_barrier
	ds_read_b128 v[132:135], v130
	ds_read_b128 v[138:141], v130 offset:1024
	ds_read_b128 v[142:145], v130 offset:2048
	ds_read_b128 v[154:157], v130 offset:3072
	v_mov_b32_e32 v188, v146
	v_mov_b32_e32 v186, v148
	ds_read_b128 v[158:161], v153 offset:32768
	ds_read_b128 v[162:165], v153 offset:33792
	ds_read_b128 v[166:169], v153 offset:34816
	ds_read_b128 v[170:173], v153 offset:35840
	ds_read_b128 v[174:177], v153 offset:36864
	ds_read_b128 v[178:181], v153 offset:37888
	ds_read_b128 v[182:185], v153 offset:38912
	ds_read_b128 v[190:193], v153 offset:39936
	v_mov_b32_e32 v187, v189
	v_lshl_add_u64 v[194:195], s[22:23], 0, v[188:189]
	s_mov_b32 m0, s34
	v_lshl_add_u64 v[194:195], v[194:195], 0, s[52:53]
	v_lshl_add_u64 v[186:187], s[22:23], 0, v[186:187]
	global_load_lds_dwordx4 v[194:195], off
	v_lshl_add_u64 v[186:187], v[186:187], 0, s[52:53]
	s_mov_b32 m0, s35
	s_nop 0
	global_load_lds_dwordx4 v[186:187], off
	s_waitcnt lgkmcnt(8)
	s_barrier
	s_waitcnt lgkmcnt(0)
	s_setprio 1
	s_waitcnt lgkmcnt(0)
	v_mfma_f32_16x16x32_bf16 v[4:7], v[132:135], v[158:161], v[4:7]
	v_mfma_f32_16x16x32_bf16 v[0:3], v[142:145], v[158:161], v[0:3]
	v_mfma_f32_16x16x32_bf16 v[20:23], v[132:135], v[166:169], v[20:23]
	v_mfma_f32_16x16x32_bf16 v[16:19], v[142:145], v[166:169], v[16:19]
	v_mfma_f32_16x16x32_bf16 v[36:39], v[132:135], v[174:177], v[36:39]
	v_mfma_f32_16x16x32_bf16 v[32:35], v[142:145], v[174:177], v[32:35]
	v_mfma_f32_16x16x32_bf16 v[52:55], v[132:135], v[182:185], v[52:55]
	v_mfma_f32_16x16x32_bf16 v[48:51], v[142:145], v[182:185], v[48:51]
	v_mfma_f32_16x16x32_bf16 v[4:7], v[138:141], v[162:165], v[4:7]
	v_mfma_f32_16x16x32_bf16 v[0:3], v[154:157], v[162:165], v[0:3]
	v_mfma_f32_16x16x32_bf16 v[20:23], v[138:141], v[170:173], v[20:23]
	v_mfma_f32_16x16x32_bf16 v[16:19], v[154:157], v[170:173], v[16:19]
	v_mfma_f32_16x16x32_bf16 v[36:39], v[138:141], v[178:181], v[36:39]
	v_mfma_f32_16x16x32_bf16 v[32:35], v[154:157], v[178:181], v[32:35]
	v_mfma_f32_16x16x32_bf16 v[52:55], v[138:141], v[190:193], v[52:55]
	v_mfma_f32_16x16x32_bf16 v[48:51], v[154:157], v[190:193], v[48:51]
	s_setprio 0
	s_barrier
	s_add_i32 s49, 0, 0x1c000
	v_add_u32_e32 v131, s49, v151
	v_mov_b32_e32 v188, v147
	v_mov_b32_e32 v186, v149
	ds_read_b128 v[202:205], v131
	ds_read_b128 v[222:225], v131 offset:1024
	ds_read_b128 v[226:229], v131 offset:2048
	ds_read_b128 v[230:233], v131 offset:3072
	s_add_i32 s48, s48, s29
	v_lshl_add_u64 v[194:195], s[24:25], 0, v[188:189]
	v_mov_b32_e32 v187, v189
	v_lshl_add_u64 v[194:195], v[194:195], 0, s[2:3]
	s_mov_b32 m0, s48
	v_lshl_add_u64 v[186:187], s[24:25], 0, v[186:187]
	s_add_i32 s47, s48, 0x2000
	global_load_lds_dwordx4 v[194:195], off
	v_lshl_add_u64 v[186:187], v[186:187], 0, s[2:3]
	s_mov_b32 m0, s47
	s_nop 0
	global_load_lds_dwordx4 v[186:187], off
	s_barrier
	s_waitcnt lgkmcnt(0)
	s_setprio 1
	s_waitcnt lgkmcnt(0)
	v_mfma_f32_16x16x32_bf16 v[12:15], v[202:205], v[158:161], v[12:15]
	v_mfma_f32_16x16x32_bf16 v[8:11], v[226:229], v[158:161], v[8:11]
	v_mfma_f32_16x16x32_bf16 v[28:31], v[202:205], v[166:169], v[28:31]
	v_mfma_f32_16x16x32_bf16 v[24:27], v[226:229], v[166:169], v[24:27]
	v_mfma_f32_16x16x32_bf16 v[44:47], v[202:205], v[174:177], v[44:47]
	v_mfma_f32_16x16x32_bf16 v[40:43], v[226:229], v[174:177], v[40:43]
	v_mfma_f32_16x16x32_bf16 v[60:63], v[202:205], v[182:185], v[60:63]
	v_mfma_f32_16x16x32_bf16 v[56:59], v[226:229], v[182:185], v[56:59]
	v_mfma_f32_16x16x32_bf16 v[12:15], v[222:225], v[162:165], v[12:15]
	v_mfma_f32_16x16x32_bf16 v[8:11], v[230:233], v[162:165], v[8:11]
	v_mfma_f32_16x16x32_bf16 v[28:31], v[222:225], v[170:173], v[28:31]
	v_mfma_f32_16x16x32_bf16 v[24:27], v[230:233], v[170:173], v[24:27]
	v_mfma_f32_16x16x32_bf16 v[44:47], v[222:225], v[178:181], v[44:47]
	v_mfma_f32_16x16x32_bf16 v[40:43], v[230:233], v[178:181], v[40:43]
	v_mfma_f32_16x16x32_bf16 v[60:63], v[222:225], v[190:193], v[60:63]
	v_mfma_f32_16x16x32_bf16 v[56:59], v[230:233], v[190:193], v[56:59]
	s_setprio 0
	v_mov_b32_e32 v188, v146
	v_mov_b32_e32 v186, v148
	s_barrier
	ds_read_b128 v[158:161], v153 offset:49152
	ds_read_b128 v[162:165], v153 offset:50176
	ds_read_b128 v[166:169], v153 offset:51200
	ds_read_b128 v[170:173], v153 offset:52224
	ds_read_b128 v[174:177], v153 offset:53248
	ds_read_b128 v[178:181], v153 offset:54272
	ds_read_b128 v[182:185], v153 offset:55296
	ds_read_b128 v[190:193], v153 offset:56320
	v_mov_b32_e32 v187, v189
	v_lshl_add_u64 v[194:195], s[22:23], 0, v[188:189]
	s_mov_b32 m0, s36
	v_lshl_add_u64 v[194:195], v[194:195], 0, s[2:3]
	v_lshl_add_u64 v[186:187], s[22:23], 0, v[186:187]
	global_load_lds_dwordx4 v[194:195], off
	v_lshl_add_u64 v[186:187], v[186:187], 0, s[2:3]
	s_mov_b32 m0, s37
	s_nop 0
	global_load_lds_dwordx4 v[186:187], off
	s_barrier
	s_waitcnt lgkmcnt(0)
	s_setprio 1
	s_waitcnt lgkmcnt(0)
	v_mfma_f32_16x16x32_bf16 v[68:71], v[132:135], v[158:161], v[68:71]
	v_mfma_f32_16x16x32_bf16 v[64:67], v[142:145], v[158:161], v[64:67]
	v_mfma_f32_16x16x32_bf16 v[84:87], v[132:135], v[166:169], v[84:87]
	v_mfma_f32_16x16x32_bf16 v[80:83], v[142:145], v[166:169], v[80:83]
	v_mfma_f32_16x16x32_bf16 v[100:103], v[132:135], v[174:177], v[100:103]
	v_mfma_f32_16x16x32_bf16 v[96:99], v[142:145], v[174:177], v[96:99]
	v_mfma_f32_16x16x32_bf16 v[120:123], v[132:135], v[182:185], v[120:123]
	v_mfma_f32_16x16x32_bf16 v[116:119], v[142:145], v[182:185], v[116:119]
	v_mfma_f32_16x16x32_bf16 v[68:71], v[138:141], v[162:165], v[68:71]
	v_mfma_f32_16x16x32_bf16 v[64:67], v[154:157], v[162:165], v[64:67]
	v_mfma_f32_16x16x32_bf16 v[84:87], v[138:141], v[170:173], v[84:87]
	v_mfma_f32_16x16x32_bf16 v[80:83], v[154:157], v[170:173], v[80:83]
	v_mfma_f32_16x16x32_bf16 v[100:103], v[138:141], v[178:181], v[100:103]
	v_mfma_f32_16x16x32_bf16 v[96:99], v[154:157], v[178:181], v[96:99]
	v_mfma_f32_16x16x32_bf16 v[120:123], v[138:141], v[190:193], v[120:123]
	v_mfma_f32_16x16x32_bf16 v[116:119], v[154:157], v[190:193], v[116:119]
	s_setprio 0
	s_barrier
	v_mov_b32_e32 v188, v147
	v_mov_b32_e32 v132, v149
	s_add_i32 s22, s49, s29
	v_lshl_add_u64 v[134:135], s[24:25], 0, v[188:189]
	v_mov_b32_e32 v133, v189
	v_lshl_add_u64 v[134:135], v[134:135], 0, s[54:55]
	s_mov_b32 m0, s22
	v_lshl_add_u64 v[132:133], s[24:25], 0, v[132:133]
	s_add_i32 s23, s22, 0x2000
	global_load_lds_dwordx4 v[134:135], off
	v_lshl_add_u64 v[132:133], v[132:133], 0, s[54:55]
	s_mov_b32 m0, s23
	s_nop 0
	global_load_lds_dwordx4 v[132:133], off
	s_waitcnt vmcnt(6)
	s_barrier
	s_setprio 1
	v_mfma_f32_16x16x32_bf16 v[76:79], v[202:205], v[158:161], v[76:79]
	v_mfma_f32_16x16x32_bf16 v[72:75], v[226:229], v[158:161], v[72:75]
	v_mfma_f32_16x16x32_bf16 v[92:95], v[202:205], v[166:169], v[92:95]
	v_mfma_f32_16x16x32_bf16 v[88:91], v[226:229], v[166:169], v[88:91]
	v_mfma_f32_16x16x32_bf16 v[108:111], v[202:205], v[174:177], v[108:111]
	v_mfma_f32_16x16x32_bf16 v[104:107], v[226:229], v[174:177], v[104:107]
	v_mfma_f32_16x16x32_bf16 v[124:127], v[202:205], v[182:185], v[124:127]
	v_mfma_f32_16x16x32_bf16 v[112:115], v[226:229], v[182:185], v[112:115]
	v_mfma_f32_16x16x32_bf16 v[76:79], v[222:225], v[162:165], v[76:79]
	v_mfma_f32_16x16x32_bf16 v[72:75], v[230:233], v[162:165], v[72:75]
	v_mfma_f32_16x16x32_bf16 v[92:95], v[222:225], v[170:173], v[92:95]
	v_mfma_f32_16x16x32_bf16 v[88:91], v[230:233], v[170:173], v[88:91]
	v_mfma_f32_16x16x32_bf16 v[108:111], v[222:225], v[178:181], v[108:111]
	v_mfma_f32_16x16x32_bf16 v[104:107], v[230:233], v[178:181], v[104:107]
	v_mfma_f32_16x16x32_bf16 v[124:127], v[222:225], v[190:193], v[124:127]
	v_mfma_f32_16x16x32_bf16 v[112:115], v[230:233], v[190:193], v[112:115]
	s_setprio 0
	s_add_i32 s13, s13, 2
	s_add_u32 s6, s6, 0x100
	s_addc_u32 s7, s7, 0
	s_cmp_lt_u32 s13, 4
	s_barrier
	s_cbranch_scc1 .LBB0_357
	ds_read_b128 v[132:135], v128
	ds_read_b128 v[138:141], v128 offset:1024
	ds_read_b128 v[142:145], v128 offset:2048
	ds_read_b128 v[154:157], v128 offset:3072
	s_add_u32 s6, s10, 0x20380
	v_mov_b32_e32 v128, v148
	v_mov_b32_e32 v186, v146
	s_addc_u32 s7, s11, 0
	s_mov_b32 m0, s15
	ds_read_b128 v[158:161], v153
	ds_read_b128 v[162:165], v153 offset:1024
	ds_read_b128 v[166:169], v153 offset:2048
	ds_read_b128 v[170:173], v153 offset:3072
	ds_read_b128 v[174:177], v153 offset:4096
	ds_read_b128 v[178:181], v153 offset:5120
	ds_read_b128 v[182:185], v153 offset:6144
	ds_read_b128 v[190:193], v153 offset:7168
	s_nop 0
	global_load_lds_dwordx4 v186, s[6:7]
	s_mov_b32 m0, s17
	s_nop 0
	global_load_lds_dwordx4 v128, s[6:7]
	s_waitcnt lgkmcnt(8)
	s_barrier
	s_waitcnt lgkmcnt(0)
	s_setprio 1
	s_waitcnt lgkmcnt(0)
	v_mfma_f32_16x16x32_bf16 v[4:7], v[132:135], v[158:161], v[4:7]
	v_mfma_f32_16x16x32_bf16 v[0:3], v[142:145], v[158:161], v[0:3]
	v_mfma_f32_16x16x32_bf16 v[20:23], v[132:135], v[166:169], v[20:23]
	v_mfma_f32_16x16x32_bf16 v[16:19], v[142:145], v[166:169], v[16:19]
	v_mfma_f32_16x16x32_bf16 v[36:39], v[132:135], v[174:177], v[36:39]
	v_mfma_f32_16x16x32_bf16 v[32:35], v[142:145], v[174:177], v[32:35]
	v_mfma_f32_16x16x32_bf16 v[52:55], v[132:135], v[182:185], v[52:55]
	v_mfma_f32_16x16x32_bf16 v[48:51], v[142:145], v[182:185], v[48:51]
	v_mfma_f32_16x16x32_bf16 v[4:7], v[138:141], v[162:165], v[4:7]
	v_mfma_f32_16x16x32_bf16 v[0:3], v[154:157], v[162:165], v[0:3]
	v_mfma_f32_16x16x32_bf16 v[20:23], v[138:141], v[170:173], v[20:23]
	v_mfma_f32_16x16x32_bf16 v[16:19], v[154:157], v[170:173], v[16:19]
	v_mfma_f32_16x16x32_bf16 v[36:39], v[138:141], v[178:181], v[36:39]
	v_mfma_f32_16x16x32_bf16 v[32:35], v[154:157], v[178:181], v[32:35]
	v_mfma_f32_16x16x32_bf16 v[52:55], v[138:141], v[190:193], v[52:55]
	v_mfma_f32_16x16x32_bf16 v[48:51], v[154:157], v[190:193], v[48:51]
	s_setprio 0
	s_barrier
	ds_read_b128 v[202:205], v129
	ds_read_b128 v[222:225], v129 offset:1024
	ds_read_b128 v[226:229], v129 offset:2048
	ds_read_b128 v[230:233], v129 offset:3072
	v_mov_b32_e32 v128, v149
	v_mov_b32_e32 v129, v147
	s_mov_b32 m0, s43
	s_nop 0
	global_load_lds_dwordx4 v129, s[20:21]
	s_mov_b32 m0, s44
	s_nop 0
	global_load_lds_dwordx4 v128, s[20:21]
	s_barrier
	s_waitcnt lgkmcnt(0)
	s_setprio 1
	s_waitcnt lgkmcnt(0)
	v_mfma_f32_16x16x32_bf16 v[12:15], v[202:205], v[158:161], v[12:15]
	v_mfma_f32_16x16x32_bf16 v[8:11], v[226:229], v[158:161], v[8:11]
	v_mfma_f32_16x16x32_bf16 v[28:31], v[202:205], v[166:169], v[28:31]
	v_mfma_f32_16x16x32_bf16 v[24:27], v[226:229], v[166:169], v[24:27]
	v_mfma_f32_16x16x32_bf16 v[44:47], v[202:205], v[174:177], v[44:47]
	v_mfma_f32_16x16x32_bf16 v[40:43], v[226:229], v[174:177], v[40:43]
	v_mfma_f32_16x16x32_bf16 v[60:63], v[202:205], v[182:185], v[60:63]
	v_mfma_f32_16x16x32_bf16 v[56:59], v[226:229], v[182:185], v[56:59]
	v_mfma_f32_16x16x32_bf16 v[12:15], v[222:225], v[162:165], v[12:15]
	v_mfma_f32_16x16x32_bf16 v[8:11], v[230:233], v[162:165], v[8:11]
	v_mfma_f32_16x16x32_bf16 v[28:31], v[222:225], v[170:173], v[28:31]
	v_mfma_f32_16x16x32_bf16 v[24:27], v[230:233], v[170:173], v[24:27]
	v_mfma_f32_16x16x32_bf16 v[44:47], v[222:225], v[178:181], v[44:47]
	v_mfma_f32_16x16x32_bf16 v[40:43], v[230:233], v[178:181], v[40:43]
	v_mfma_f32_16x16x32_bf16 v[60:63], v[222:225], v[190:193], v[60:63]
	v_mfma_f32_16x16x32_bf16 v[56:59], v[230:233], v[190:193], v[56:59]
	s_setprio 0
	v_mov_b32_e32 v128, v148
	v_mov_b32_e32 v129, v146
	s_mov_b32 m0, s30
	s_barrier
	ds_read_b128 v[158:161], v153 offset:16384
	ds_read_b128 v[162:165], v153 offset:17408
	ds_read_b128 v[166:169], v153 offset:18432
	ds_read_b128 v[170:173], v153 offset:19456
	ds_read_b128 v[174:177], v153 offset:20480
	ds_read_b128 v[178:181], v153 offset:21504
	ds_read_b128 v[182:185], v153 offset:22528
	ds_read_b128 v[190:193], v153 offset:23552
	s_nop 0
	global_load_lds_dwordx4 v129, s[18:19]
	s_mov_b32 m0, s31
	s_nop 0
	global_load_lds_dwordx4 v128, s[18:19]
	s_barrier
	s_waitcnt lgkmcnt(0)
	s_setprio 1
	s_waitcnt lgkmcnt(0)
	v_mfma_f32_16x16x32_bf16 v[68:71], v[132:135], v[158:161], v[68:71]
	v_mfma_f32_16x16x32_bf16 v[64:67], v[142:145], v[158:161], v[64:67]
	v_mfma_f32_16x16x32_bf16 v[84:87], v[132:135], v[166:169], v[84:87]
	v_mfma_f32_16x16x32_bf16 v[80:83], v[142:145], v[166:169], v[80:83]
	v_mfma_f32_16x16x32_bf16 v[100:103], v[132:135], v[174:177], v[100:103]
	v_mfma_f32_16x16x32_bf16 v[96:99], v[142:145], v[174:177], v[96:99]
	v_mfma_f32_16x16x32_bf16 v[120:123], v[132:135], v[182:185], v[120:123]
	v_mfma_f32_16x16x32_bf16 v[116:119], v[142:145], v[182:185], v[116:119]
	v_mfma_f32_16x16x32_bf16 v[68:71], v[138:141], v[162:165], v[68:71]
	v_mfma_f32_16x16x32_bf16 v[64:67], v[154:157], v[162:165], v[64:67]
	v_mfma_f32_16x16x32_bf16 v[84:87], v[138:141], v[170:173], v[84:87]
	v_mfma_f32_16x16x32_bf16 v[80:83], v[154:157], v[170:173], v[80:83]
	v_mfma_f32_16x16x32_bf16 v[100:103], v[138:141], v[178:181], v[100:103]
	v_mfma_f32_16x16x32_bf16 v[96:99], v[154:157], v[178:181], v[96:99]
	v_mfma_f32_16x16x32_bf16 v[120:123], v[138:141], v[190:193], v[120:123]
	v_mfma_f32_16x16x32_bf16 v[116:119], v[154:157], v[190:193], v[116:119]
	s_setprio 0
	s_barrier
	s_add_u32 s6, s20, 0x20000
	v_mov_b32_e32 v128, v149
	v_mov_b32_e32 v129, v147
	s_addc_u32 s7, s21, 0
	s_mov_b32 m0, s45
	s_nop 0
	global_load_lds_dwordx4 v129, s[6:7]
	s_mov_b32 m0, s46
	s_nop 0
	global_load_lds_dwordx4 v128, s[6:7]
	s_waitcnt vmcnt(6)
	s_barrier
	s_setprio 1
	v_mfma_f32_16x16x32_bf16 v[76:79], v[202:205], v[158:161], v[76:79]
	v_mfma_f32_16x16x32_bf16 v[72:75], v[226:229], v[158:161], v[72:75]
	v_mfma_f32_16x16x32_bf16 v[92:95], v[202:205], v[166:169], v[92:95]
	v_mfma_f32_16x16x32_bf16 v[88:91], v[226:229], v[166:169], v[88:91]
	v_mfma_f32_16x16x32_bf16 v[108:111], v[202:205], v[174:177], v[108:111]
	v_mfma_f32_16x16x32_bf16 v[104:107], v[226:229], v[174:177], v[104:107]
	v_mfma_f32_16x16x32_bf16 v[124:127], v[202:205], v[182:185], v[124:127]
	v_mfma_f32_16x16x32_bf16 v[112:115], v[226:229], v[182:185], v[112:115]
	v_mfma_f32_16x16x32_bf16 v[76:79], v[222:225], v[162:165], v[76:79]
	v_mfma_f32_16x16x32_bf16 v[72:75], v[230:233], v[162:165], v[72:75]
	v_mfma_f32_16x16x32_bf16 v[92:95], v[222:225], v[170:173], v[92:95]
	v_mfma_f32_16x16x32_bf16 v[88:91], v[230:233], v[170:173], v[88:91]
	v_mfma_f32_16x16x32_bf16 v[108:111], v[222:225], v[178:181], v[108:111]
	v_mfma_f32_16x16x32_bf16 v[104:107], v[230:233], v[178:181], v[104:107]
	v_mfma_f32_16x16x32_bf16 v[124:127], v[222:225], v[190:193], v[124:127]
	v_mfma_f32_16x16x32_bf16 v[112:115], v[230:233], v[190:193], v[112:115]
	s_setprio 0
	s_barrier
	ds_read_b128 v[132:135], v130
	ds_read_b128 v[138:141], v130 offset:1024
	ds_read_b128 v[142:145], v130 offset:2048
	ds_read_b128 v[154:157], v130 offset:3072
	s_add_u32 s6, s18, 0x20000
	v_mov_b32_e32 v128, v148
	v_mov_b32_e32 v129, v146
	s_addc_u32 s7, s19, 0
	s_mov_b32 m0, s34
	ds_read_b128 v[158:161], v153 offset:32768
	ds_read_b128 v[162:165], v153 offset:33792
	ds_read_b128 v[166:169], v153 offset:34816
	ds_read_b128 v[170:173], v153 offset:35840
	ds_read_b128 v[174:177], v153 offset:36864
	ds_read_b128 v[178:181], v153 offset:37888
	ds_read_b128 v[182:185], v153 offset:38912
	ds_read_b128 v[190:193], v153 offset:39936
	s_nop 0
	global_load_lds_dwordx4 v129, s[6:7]
	s_mov_b32 m0, s35
	s_nop 0
	global_load_lds_dwordx4 v128, s[6:7]
	s_waitcnt lgkmcnt(8)
	s_barrier
	s_waitcnt lgkmcnt(0)
	s_setprio 1
	s_waitcnt lgkmcnt(0)
	v_mfma_f32_16x16x32_bf16 v[4:7], v[132:135], v[158:161], v[4:7]
	v_mfma_f32_16x16x32_bf16 v[0:3], v[142:145], v[158:161], v[0:3]
	v_mfma_f32_16x16x32_bf16 v[20:23], v[132:135], v[166:169], v[20:23]
	v_mfma_f32_16x16x32_bf16 v[16:19], v[142:145], v[166:169], v[16:19]
	v_mfma_f32_16x16x32_bf16 v[36:39], v[132:135], v[174:177], v[36:39]
	v_mfma_f32_16x16x32_bf16 v[32:35], v[142:145], v[174:177], v[32:35]
	v_mfma_f32_16x16x32_bf16 v[52:55], v[132:135], v[182:185], v[52:55]
	v_mfma_f32_16x16x32_bf16 v[48:51], v[142:145], v[182:185], v[48:51]
	v_mfma_f32_16x16x32_bf16 v[4:7], v[138:141], v[162:165], v[4:7]
	v_mfma_f32_16x16x32_bf16 v[0:3], v[154:157], v[162:165], v[0:3]
	v_mfma_f32_16x16x32_bf16 v[20:23], v[138:141], v[170:173], v[20:23]
	v_mfma_f32_16x16x32_bf16 v[16:19], v[154:157], v[170:173], v[16:19]
	v_mfma_f32_16x16x32_bf16 v[36:39], v[138:141], v[178:181], v[36:39]
	v_mfma_f32_16x16x32_bf16 v[32:35], v[154:157], v[178:181], v[32:35]
	v_mfma_f32_16x16x32_bf16 v[52:55], v[138:141], v[190:193], v[52:55]
	v_mfma_f32_16x16x32_bf16 v[48:51], v[154:157], v[190:193], v[48:51]
	s_setprio 0
	s_barrier
	v_mov_b32_e32 v186, v149
	v_mov_b32_e32 v188, v147
	ds_read_b128 v[202:205], v131
	ds_read_b128 v[222:225], v131 offset:1024
	ds_read_b128 v[226:229], v131 offset:2048
	ds_read_b128 v[128:131], v131 offset:3072
	s_mov_b64 s[6:7], 0x80
	v_lshl_add_u64 v[194:195], s[20:21], 0, v[188:189]
	v_mov_b32_e32 v187, v189
	s_mov_b32 m0, s48
	v_lshl_add_u64 v[194:195], v[194:195], 0, s[6:7]
	v_lshl_add_u64 v[186:187], s[20:21], 0, v[186:187]
	global_load_lds_dwordx4 v[194:195], off
	v_lshl_add_u64 v[186:187], v[186:187], 0, s[6:7]
	s_mov_b32 m0, s47
	s_nop 0
	global_load_lds_dwordx4 v[186:187], off
	s_barrier
	s_waitcnt lgkmcnt(0)
	s_setprio 1
	s_waitcnt lgkmcnt(0)
	v_mfma_f32_16x16x32_bf16 v[12:15], v[202:205], v[158:161], v[12:15]
	v_mfma_f32_16x16x32_bf16 v[8:11], v[226:229], v[158:161], v[8:11]
	v_mfma_f32_16x16x32_bf16 v[28:31], v[202:205], v[166:169], v[28:31]
	v_mfma_f32_16x16x32_bf16 v[24:27], v[226:229], v[166:169], v[24:27]
	v_mfma_f32_16x16x32_bf16 v[44:47], v[202:205], v[174:177], v[44:47]
	v_mfma_f32_16x16x32_bf16 v[40:43], v[226:229], v[174:177], v[40:43]
	v_mfma_f32_16x16x32_bf16 v[60:63], v[202:205], v[182:185], v[60:63]
	v_mfma_f32_16x16x32_bf16 v[56:59], v[226:229], v[182:185], v[56:59]
	v_mfma_f32_16x16x32_bf16 v[12:15], v[222:225], v[162:165], v[12:15]
	v_mfma_f32_16x16x32_bf16 v[8:11], v[128:131], v[162:165], v[8:11]
	v_mfma_f32_16x16x32_bf16 v[28:31], v[222:225], v[170:173], v[28:31]
	v_mfma_f32_16x16x32_bf16 v[24:27], v[128:131], v[170:173], v[24:27]
	v_mfma_f32_16x16x32_bf16 v[44:47], v[222:225], v[178:181], v[44:47]
	v_mfma_f32_16x16x32_bf16 v[40:43], v[128:131], v[178:181], v[40:43]
	v_mfma_f32_16x16x32_bf16 v[60:63], v[222:225], v[190:193], v[60:63]
	v_mfma_f32_16x16x32_bf16 v[56:59], v[128:131], v[190:193], v[56:59]
	s_setprio 0
	v_mov_b32_e32 v186, v148
	v_mov_b32_e32 v188, v146
	s_barrier
	ds_read_b128 v[158:161], v153 offset:49152
	ds_read_b128 v[162:165], v153 offset:50176
	ds_read_b128 v[166:169], v153 offset:51200
	ds_read_b128 v[170:173], v153 offset:52224
	ds_read_b128 v[174:177], v153 offset:53248
	ds_read_b128 v[178:181], v153 offset:54272
	ds_read_b128 v[182:185], v153 offset:55296
	ds_read_b128 v[190:193], v153 offset:56320
	v_mov_b32_e32 v187, v189
	v_lshl_add_u64 v[194:195], s[18:19], 0, v[188:189]
	s_mov_b32 m0, s36
	v_lshl_add_u64 v[194:195], v[194:195], 0, s[6:7]
	v_lshl_add_u64 v[186:187], s[18:19], 0, v[186:187]
	global_load_lds_dwordx4 v[194:195], off
	v_lshl_add_u64 v[186:187], v[186:187], 0, s[6:7]
	s_mov_b32 m0, s37
	s_nop 0
	global_load_lds_dwordx4 v[186:187], off
	s_barrier
	s_waitcnt lgkmcnt(0)
	s_setprio 1
	s_waitcnt lgkmcnt(0)
	v_mfma_f32_16x16x32_bf16 v[68:71], v[132:135], v[158:161], v[68:71]
	v_mfma_f32_16x16x32_bf16 v[64:67], v[142:145], v[158:161], v[64:67]
	v_mfma_f32_16x16x32_bf16 v[84:87], v[132:135], v[166:169], v[84:87]
	v_mfma_f32_16x16x32_bf16 v[80:83], v[142:145], v[166:169], v[80:83]
	v_mfma_f32_16x16x32_bf16 v[100:103], v[132:135], v[174:177], v[100:103]
	v_mfma_f32_16x16x32_bf16 v[96:99], v[142:145], v[174:177], v[96:99]
	v_mfma_f32_16x16x32_bf16 v[120:123], v[132:135], v[182:185], v[120:123]
	v_mfma_f32_16x16x32_bf16 v[116:119], v[142:145], v[182:185], v[116:119]
	v_mfma_f32_16x16x32_bf16 v[68:71], v[138:141], v[162:165], v[68:71]
	v_mfma_f32_16x16x32_bf16 v[64:67], v[154:157], v[162:165], v[64:67]
	v_mfma_f32_16x16x32_bf16 v[84:87], v[138:141], v[170:173], v[84:87]
	v_mfma_f32_16x16x32_bf16 v[80:83], v[154:157], v[170:173], v[80:83]
	v_mfma_f32_16x16x32_bf16 v[100:103], v[138:141], v[178:181], v[100:103]
	v_mfma_f32_16x16x32_bf16 v[96:99], v[154:157], v[178:181], v[96:99]
	v_mfma_f32_16x16x32_bf16 v[120:123], v[138:141], v[190:193], v[120:123]
	v_mfma_f32_16x16x32_bf16 v[116:119], v[154:157], v[190:193], v[116:119]
	s_setprio 0
	s_barrier
	s_add_u32 s6, s20, 0x20080
	v_mov_b32_e32 v132, v149
	v_mov_b32_e32 v133, v147
	s_addc_u32 s7, s21, 0
	s_mov_b32 m0, s22
	s_nop 0
	global_load_lds_dwordx4 v133, s[6:7]
	s_mov_b32 m0, s23
	s_nop 0
	global_load_lds_dwordx4 v132, s[6:7]
	s_waitcnt vmcnt(6)
	s_barrier
; __device__ __forceinline__ unsigned cvt_pk_bf16(float lo, float hi) { unsigned r; asm("v_cvt_pk_bf16_f32 %0, %1, %2" : "=v"(r) : "v"(lo), "v"(hi)); return r; }
; __device__ __forceinline__ float bf_lo(unsigned w) { return __uint_as_float(w << 16); }
; __device__ __forceinline__ float bf_hi(unsigned w) { return __uint_as_float(w & 0xffff0000u); }
;     __device__ __forceinline__ void operator()(f32x4 (&acc)[2][2][4][2], const Unit& u, int wr, int wc, int fr, int fq) const {
;         const int row0 = u.pm * BM + wr * 64 + fr, col0 = u.pn * BM + wc * 32 + 8 * fq;
;         const bool fin = (u.br == 2);
;         const int tidl = (wr * 4 + wc) * 64 + fq * 16 + fr;
;         const u32x4* gn = GT + ((size_t)((u.br * 64 + u.pm) * 4 + u.pn) * 16) * 512 + tidl;
;         const u32x4* gd = gn + (size_t)64 * 4 * 16 * 512;
; #pragma unroll
;         for (int ai = 0; ai < 2; ++ai)
; #pragma unroll
;             for (int m = 0; m < 4; ++m) { const size_t row = (size_t)(row0 + ai * HALF + m * 16);
; #pragma unroll
;                 for (int bj = 0; bj < 2; ++bj) { const size_t so = (size_t)((ai * 4 + m) * 2 + bj) * 512;
;                     const u32x4 zn = gn[so]; u32x4 zd = zn; if (!fin) zd = gd[so];
;                     float f[8];
; #pragma unroll
;                     for (int q = 0; q < 4; ++q) { f[2 * q] = fin ? bf_lo(zn[q]) : bf_lo(zn[q]) * __builtin_amdgcn_rcpf(bf_lo(zd[q])); f[2 * q + 1] = fin ? bf_hi(zn[q]) : bf_hi(zn[q]) * __builtin_amdgcn_rcpf(bf_hi(zd[q])); }
;                     f32x4 v0 = acc[ai][bj][m][0], v1 = acc[ai][bj][m][1];
;                     v0[0] *= f[0]; v0[1] *= f[1]; v0[2] *= f[2]; v0[3] *= f[3]; v1[0] *= f[4]; v1[1] *= f[5]; v1[2] *= f[6]; v1[3] *= f[7];
;                     acc[ai][bj][m][0] = v0; acc[ai][bj][m][1] = v1;
;                     if (fin) { u32x4 w; w.x = cvt_pk_bf16(v0[0], v0[1]); w.y = cvt_pk_bf16(v0[2], v0[3]); w.z = cvt_pk_bf16(v1[0], v1[1]); w.w = cvt_pk_bf16(v1[2], v1[3]);
;                         *(u32x4*)(O + row * DM + col0 + bj * HALF) = w; } }
;                 if (m & 1) { asm volatile("" ::: "memory"); __builtin_amdgcn_sched_barrier(0); } }
	s_setprio 1
	v_mfma_f32_16x16x32_bf16 v[76:79], v[202:205], v[158:161], v[76:79]
	v_mfma_f32_16x16x32_bf16 v[72:75], v[226:229], v[158:161], v[72:75]
	v_mfma_f32_16x16x32_bf16 v[92:95], v[202:205], v[166:169], v[92:95]
	v_mfma_f32_16x16x32_bf16 v[88:91], v[226:229], v[166:169], v[88:91]
	v_mfma_f32_16x16x32_bf16 v[108:111], v[202:205], v[174:177], v[108:111]
	v_mfma_f32_16x16x32_bf16 v[104:107], v[226:229], v[174:177], v[104:107]
	v_mfma_f32_16x16x32_bf16 v[124:127], v[202:205], v[182:185], v[124:127]
	v_mfma_f32_16x16x32_bf16 v[112:115], v[226:229], v[182:185], v[112:115]
	v_mfma_f32_16x16x32_bf16 v[76:79], v[222:225], v[162:165], v[76:79]
	v_mfma_f32_16x16x32_bf16 v[72:75], v[128:131], v[162:165], v[72:75]
	v_mfma_f32_16x16x32_bf16 v[92:95], v[222:225], v[170:173], v[92:95]
	v_mfma_f32_16x16x32_bf16 v[88:91], v[128:131], v[170:173], v[88:91]
	v_mfma_f32_16x16x32_bf16 v[108:111], v[222:225], v[178:181], v[108:111]
	v_mfma_f32_16x16x32_bf16 v[104:107], v[128:131], v[178:181], v[104:107]
	v_mfma_f32_16x16x32_bf16 v[124:127], v[222:225], v[190:193], v[124:127]
	v_mfma_f32_16x16x32_bf16 v[112:115], v[128:131], v[190:193], v[112:115]
	s_setprio 0
	s_cmp_eq_u32 s42, 2
	s_cselect_b64 s[6:7], -1, 0
	s_cmp_lg_u32 s42, 2
	s_cselect_b64 s[22:23], -1, 0
	s_lshl_b32 s9, s41, 2
	s_lshl_b32 s8, s42, 8
	s_add_i32 s9, s9, s33
	s_add_i32 s8, s9, s8
	s_ashr_i32 s9, s8, 31
	s_lshl_b64 s[8:9], s[8:9], 17
	v_lshl_add_u64 v[138:139], v[136:137], 0, s[8:9]
	s_barrier
	v_mov_b32_e32 v200, 0x2000000
	v_mov_b32_e32 v201, 0
	v_cndmask_b32_e64 v200, v200, 0, s[6:7]
	global_load_dwordx4 v[156:159], v[138:139], off
	v_lshl_add_u64 v[198:199], v[138:139], 0, v[200:201]
	global_load_dwordx4 v[160:163], v[198:199], off
	v_add_co_u32_e32 v198, vcc, 0x2000, v138
	s_nop 1
	v_addc_co_u32_e32 v199, vcc, 0, v139, vcc
	global_load_dwordx4 v[164:167], v[198:199], off
	v_lshl_add_u64 v[198:199], v[198:199], 0, v[200:201]
	global_load_dwordx4 v[168:171], v[198:199], off
	v_add_co_u32_e32 v198, vcc, 0x4000, v138
	s_nop 1
	v_addc_co_u32_e32 v199, vcc, 0, v139, vcc
	global_load_dwordx4 v[172:175], v[198:199], off
	v_lshl_add_u64 v[198:199], v[198:199], 0, v[200:201]
	global_load_dwordx4 v[176:179], v[198:199], off
	v_add_co_u32_e32 v198, vcc, 0x6000, v138
	s_nop 1
	v_addc_co_u32_e32 v199, vcc, 0, v139, vcc
	global_load_dwordx4 v[180:183], v[198:199], off
	v_lshl_add_u64 v[198:199], v[198:199], 0, v[200:201]
	global_load_dwordx4 v[184:187], v[198:199], off
	v_add_co_u32_e32 v198, vcc, 0x8000, v138
	s_nop 1
	v_addc_co_u32_e32 v199, vcc, 0, v139, vcc
	global_load_dwordx4 v[226:229], v[198:199], off
	v_lshl_add_u64 v[198:199], v[198:199], 0, v[200:201]
	global_load_dwordx4 v[230:233], v[198:199], off
	v_add_co_u32_e32 v198, vcc, 0xa000, v138
	s_nop 1
	v_addc_co_u32_e32 v199, vcc, 0, v139, vcc
	global_load_dwordx4 v[234:237], v[198:199], off
	v_lshl_add_u64 v[198:199], v[198:199], 0, v[200:201]
	global_load_dwordx4 v[238:241], v[198:199], off
	v_add_co_u32_e32 v198, vcc, 0xc000, v138
	s_nop 1
	v_addc_co_u32_e32 v199, vcc, 0, v139, vcc
	global_load_dwordx4 v[242:245], v[198:199], off
	v_lshl_add_u64 v[198:199], v[198:199], 0, v[200:201]
	global_load_dwordx4 v[246:249], v[198:199], off
	v_add_co_u32_e32 v198, vcc, 0xe000, v138
	s_nop 1
	v_addc_co_u32_e32 v199, vcc, 0, v139, vcc
	global_load_dwordx4 v[202:205], v[198:199], off
	v_lshl_add_u64 v[198:199], v[198:199], 0, v[200:201]
	global_load_dwordx4 v[194:197], v[198:199], off
	s_waitcnt vmcnt(14)
	v_mov_b64_e32 v[128:129], v[156:157]
	v_mov_b64_e32 v[130:131], v[158:159]
	s_and_b64 vcc, exec, s[6:7]
	v_mov_b64_e32 v[132:133], v[160:161]
	v_mov_b64_e32 v[134:135], v[162:163]
	v_add_co_u32_e32 v198, vcc, 0x10000, v138
	s_nop 1
	v_addc_co_u32_e32 v199, vcc, 0, v139, vcc
	global_load_dwordx4 v[156:159], v[198:199], off
	v_lshl_add_u64 v[198:199], v[198:199], 0, v[200:201]
	global_load_dwordx4 v[160:163], v[198:199], off
.LBB0_360:
	v_lshlrev_b32_e32 v154, 16, v132
	v_and_b32_e32 v132, 0xffff0000, v132
	v_rcp_f32_e32 v132, v132
	v_lshlrev_b32_e32 v155, 16, v128
	v_and_b32_e32 v128, 0xffff0000, v128
	v_rcp_f32_e32 v154, v154
	v_mul_f32_e32 v132, v132, v128
	v_cndmask_b32_e64 v128, v132, v128, s[6:7]
	v_lshlrev_b32_e32 v132, 16, v133
	v_and_b32_e32 v133, 0xffff0000, v133
	v_rcp_f32_e32 v133, v133
	v_mul_f32_e32 v154, v154, v155
	v_cndmask_b32_e64 v154, v154, v155, s[6:7]
	v_lshlrev_b32_e32 v155, 16, v129
	v_and_b32_e32 v129, 0xffff0000, v129
	v_rcp_f32_e32 v132, v132
	v_mul_f32_e32 v133, v133, v129
	v_cndmask_b32_e64 v129, v133, v129, s[6:7]
	v_lshlrev_b32_e32 v133, 16, v134
	v_and_b32_e32 v134, 0xffff0000, v134
	v_rcp_f32_e32 v134, v134
	v_mul_f32_e32 v132, v132, v155
	v_cndmask_b32_e64 v132, v132, v155, s[6:7]
	v_lshlrev_b32_e32 v155, 16, v130
	v_and_b32_e32 v130, 0xffff0000, v130
	v_rcp_f32_e32 v133, v133
	v_mul_f32_e32 v134, v134, v130
	v_cndmask_b32_e64 v130, v134, v130, s[6:7]
	v_lshlrev_b32_e32 v134, 16, v135
	v_and_b32_e32 v135, 0xffff0000, v135
	v_rcp_f32_e32 v134, v134
	v_rcp_f32_e32 v135, v135
	v_lshl_add_u32 v142, s41, 8, v150
	v_mul_f32_e32 v133, v133, v155
	v_ashrrev_i32_e32 v143, 31, v142
	v_cndmask_b32_e64 v133, v133, v155, s[6:7]
	v_lshlrev_b32_e32 v155, 16, v131
	v_and_b32_e32 v131, 0xffff0000, v131
	v_readlane_b32 s10, v253, 61
	v_lshl_or_b32 v140, s33, 8, v152
	v_lshlrev_b64 v[144:145], 11, v[142:143]
	v_mul_f32_e32 v134, v134, v155
	v_mul_f32_e32 v135, v135, v131
	v_mul_f32_e32 v5, v5, v128
	v_cndmask_b32_e64 v128, 0, 1, s[6:7]
	v_readlane_b32 s11, v253, 62
	v_ashrrev_i32_e32 v141, 31, v140
	v_cndmask_b32_e64 v134, v134, v155, s[6:7]
	v_cndmask_b32_e64 v131, v135, v131, s[6:7]
	v_mul_f32_e32 v7, v7, v129
	v_cmp_ne_u32_e64 s[8:9], 1, v128
	v_lshl_add_u64 v[128:129], s[10:11], 0, v[144:145]
	v_mul_f32_e32 v4, v4, v154
	v_mul_f32_e32 v6, v6, v132
	v_mul_f32_e32 v0, v0, v133
	v_mul_f32_e32 v1, v1, v130
	v_mul_f32_e32 v2, v2, v134
	v_mul_f32_e32 v3, v3, v131
	s_andn2_b64 vcc, exec, s[6:7]
	v_lshl_add_u64 v[144:145], v[140:141], 1, v[128:129]
	s_cbranch_vccnz .LBB0_362
	v_cvt_pk_bf16_f32 v128, v4, v5
	v_cvt_pk_bf16_f32 v129, v6, v7
	v_cvt_pk_bf16_f32 v130, v0, v1
	v_cvt_pk_bf16_f32 v131, v2, v3
	global_store_dwordx4 v[144:145], v[128:131], off
; __device__ __forceinline__ unsigned cvt_pk_bf16(float lo, float hi) { unsigned r; asm("v_cvt_pk_bf16_f32 %0, %1, %2" : "=v"(r) : "v"(lo), "v"(hi)); return r; }
; __device__ __forceinline__ float bf_lo(unsigned w) { return __uint_as_float(w << 16); }
; __device__ __forceinline__ float bf_hi(unsigned w) { return __uint_as_float(w & 0xffff0000u); }
;     __device__ __forceinline__ void operator()(f32x4 (&acc)[2][2][4][2], const Unit& u, int wr, int wc, int fr, int fq) const {
;     ...
;         for (int ai = 0; ai < 2; ++ai)
; #pragma unroll
;             for (int m = 0; m < 4; ++m) { const size_t row = (size_t)(row0 + ai * HALF + m * 16);
; #pragma unroll
;                 for (int bj = 0; bj < 2; ++bj) { const size_t so = (size_t)((ai * 4 + m) * 2 + bj) * 512;
;                     const u32x4 zn = gn[so]; u32x4 zd = zn; if (!fin) zd = gd[so];
;                     float f[8];
; #pragma unroll
;                     for (int q = 0; q < 4; ++q) { f[2 * q] = fin ? bf_lo(zn[q]) : bf_lo(zn[q]) * __builtin_amdgcn_rcpf(bf_lo(zd[q])); f[2 * q + 1] = fin ? bf_hi(zn[q]) : bf_hi(zn[q]) * __builtin_amdgcn_rcpf(bf_hi(zd[q])); }
;                     f32x4 v0 = acc[ai][bj][m][0], v1 = acc[ai][bj][m][1];
;                     v0[0] *= f[0]; v0[1] *= f[1]; v0[2] *= f[2]; v0[3] *= f[3]; v1[0] *= f[4]; v1[1] *= f[5]; v1[2] *= f[6]; v1[3] *= f[7];
;                     acc[ai][bj][m][0] = v0; acc[ai][bj][m][1] = v1;
;                     if (fin) { u32x4 w; w.x = cvt_pk_bf16(v0[0], v0[1]); w.y = cvt_pk_bf16(v0[2], v0[3]); w.z = cvt_pk_bf16(v1[0], v1[1]); w.w = cvt_pk_bf16(v1[2], v1[3]);
;                         *(u32x4*)(O + row * DM + col0 + bj * HALF) = w; } }
;                 if (m & 1) { asm volatile("" ::: "memory"); __builtin_amdgcn_sched_barrier(0); } }
.LBB0_362:
	s_nop 1
	v_add_co_u32_e32 v128, vcc, 0x2000, v138
	v_cndmask_b32_e64 v132, 0, 1, s[22:23]
	s_nop 0
	v_addc_co_u32_e32 v129, vcc, 0, v139, vcc
	s_waitcnt vmcnt(14)
	v_mov_b64_e32 v[128:129], v[164:165]
	v_mov_b64_e32 v[130:131], v[166:167]
	v_cmp_ne_u32_e64 s[10:11], 1, v132
	v_readlane_b32 s66, v255, 21
	s_andn2_b64 vcc, exec, s[22:23]
	v_readlane_b32 s67, v255, 22
	v_mov_b64_e32 v[132:133], v[168:169]
	v_mov_b64_e32 v[134:135], v[170:171]
	v_add_co_u32_e32 v198, vcc, 0x12000, v138
	s_nop 1
	v_addc_co_u32_e32 v199, vcc, 0, v139, vcc
	global_load_dwordx4 v[164:167], v[198:199], off
	v_lshl_add_u64 v[198:199], v[198:199], 0, v[200:201]
	global_load_dwordx4 v[168:171], v[198:199], off
.LBB0_364:
	v_lshlrev_b32_e32 v154, 16, v132
	v_and_b32_e32 v132, 0xffff0000, v132
	v_rcp_f32_e32 v132, v132
	v_lshlrev_b32_e32 v155, 16, v128
	v_and_b32_e32 v128, 0xffff0000, v128
	v_rcp_f32_e32 v154, v154
	v_mul_f32_e32 v132, v132, v128
	v_cndmask_b32_e64 v128, v132, v128, s[6:7]
	v_lshlrev_b32_e32 v132, 16, v133
	v_and_b32_e32 v133, 0xffff0000, v133
	v_rcp_f32_e32 v133, v133
	v_mul_f32_e32 v154, v154, v155
	v_cndmask_b32_e64 v154, v154, v155, s[6:7]
	v_lshlrev_b32_e32 v155, 16, v129
	v_and_b32_e32 v129, 0xffff0000, v129
	v_rcp_f32_e32 v132, v132
	v_mul_f32_e32 v133, v133, v129
	v_cndmask_b32_e64 v129, v133, v129, s[6:7]
	v_lshlrev_b32_e32 v133, 16, v134
	v_and_b32_e32 v134, 0xffff0000, v134
	v_rcp_f32_e32 v134, v134
	v_mul_f32_e32 v132, v132, v155
	v_cndmask_b32_e64 v132, v132, v155, s[6:7]
	v_lshlrev_b32_e32 v155, 16, v130
	v_and_b32_e32 v130, 0xffff0000, v130
	v_rcp_f32_e32 v133, v133
	v_mul_f32_e32 v134, v134, v130
	v_cndmask_b32_e64 v130, v134, v130, s[6:7]
	v_lshlrev_b32_e32 v134, 16, v135
	v_and_b32_e32 v135, 0xffff0000, v135
	v_rcp_f32_e32 v134, v134
	v_rcp_f32_e32 v135, v135
	v_mul_f32_e32 v133, v133, v155
	v_cndmask_b32_e64 v133, v133, v155, s[6:7]
	v_lshlrev_b32_e32 v155, 16, v131
	v_and_b32_e32 v131, 0xffff0000, v131
	v_mul_f32_e32 v134, v134, v155
	v_mul_f32_e32 v135, v135, v131
	v_cndmask_b32_e64 v134, v134, v155, s[6:7]
	v_cndmask_b32_e64 v131, v135, v131, s[6:7]
	v_mul_f32_e32 v12, v12, v154
	v_mul_f32_e32 v13, v13, v128
	v_mul_f32_e32 v14, v14, v132
	v_mul_f32_e32 v15, v15, v129
	v_mul_f32_e32 v8, v8, v133
	v_mul_f32_e32 v9, v9, v130
	v_mul_f32_e32 v10, v10, v134
	s_and_b64 vcc, exec, s[8:9]
	v_mul_f32_e32 v11, v11, v131
	s_cbranch_vccnz .LBB0_366
	v_cvt_pk_bf16_f32 v128, v12, v13
	v_cvt_pk_bf16_f32 v129, v14, v15
	v_cvt_pk_bf16_f32 v130, v8, v9
	v_cvt_pk_bf16_f32 v131, v10, v11
	global_store_dwordx4 v[144:145], v[128:131], off offset:256
.LBB0_366:
	s_nop 1
	v_add_co_u32_e32 v128, vcc, 0x4000, v138
	s_nop 1
	v_addc_co_u32_e32 v129, vcc, 0, v139, vcc
	s_waitcnt vmcnt(14)
	v_mov_b64_e32 v[128:129], v[172:173]
	v_mov_b64_e32 v[130:131], v[174:175]
	s_and_b64 vcc, exec, s[10:11]
	v_mov_b64_e32 v[132:133], v[176:177]
	v_mov_b64_e32 v[134:135], v[178:179]
	v_add_co_u32_e32 v198, vcc, 0x14000, v138
	s_nop 1
	v_addc_co_u32_e32 v199, vcc, 0, v139, vcc
	global_load_dwordx4 v[172:175], v[198:199], off
	v_lshl_add_u64 v[198:199], v[198:199], 0, v[200:201]
	global_load_dwordx4 v[176:179], v[198:199], off
.LBB0_368:
	v_lshlrev_b32_e32 v154, 16, v132
	v_and_b32_e32 v132, 0xffff0000, v132
	v_rcp_f32_e32 v132, v132
	v_lshlrev_b32_e32 v155, 16, v128
	v_and_b32_e32 v128, 0xffff0000, v128
	v_rcp_f32_e32 v154, v154
	v_mul_f32_e32 v132, v132, v128
	v_cndmask_b32_e64 v128, v132, v128, s[6:7]
	v_lshlrev_b32_e32 v132, 16, v133
	v_and_b32_e32 v133, 0xffff0000, v133
	v_rcp_f32_e32 v133, v133
	v_mul_f32_e32 v154, v154, v155
	v_cndmask_b32_e64 v154, v154, v155, s[6:7]
	v_lshlrev_b32_e32 v155, 16, v129
	v_and_b32_e32 v129, 0xffff0000, v129
	v_rcp_f32_e32 v132, v132
	v_mul_f32_e32 v133, v133, v129
	v_cndmask_b32_e64 v129, v133, v129, s[6:7]
	v_lshlrev_b32_e32 v133, 16, v134
	v_and_b32_e32 v134, 0xffff0000, v134
	v_rcp_f32_e32 v134, v134
	v_mul_f32_e32 v132, v132, v155
	v_cndmask_b32_e64 v132, v132, v155, s[6:7]
	v_lshlrev_b32_e32 v155, 16, v130
	v_and_b32_e32 v130, 0xffff0000, v130
	v_rcp_f32_e32 v133, v133
	v_mul_f32_e32 v134, v134, v130
	v_cndmask_b32_e64 v130, v134, v130, s[6:7]
	v_lshlrev_b32_e32 v134, 16, v135
	v_and_b32_e32 v135, 0xffff0000, v135
	v_rcp_f32_e32 v134, v134
	v_rcp_f32_e32 v135, v135
	v_or_b32_e32 v144, 16, v142
	v_mul_f32_e32 v133, v133, v155
	v_ashrrev_i32_e32 v145, 31, v144
	v_cndmask_b32_e64 v133, v133, v155, s[6:7]
	v_lshlrev_b32_e32 v155, 16, v131
	v_and_b32_e32 v131, 0xffff0000, v131
	v_readlane_b32 s22, v253, 61
	v_lshlrev_b64 v[144:145], 11, v[144:145]
	v_mul_f32_e32 v134, v134, v155
	v_mul_f32_e32 v135, v135, v131
	v_readlane_b32 s23, v253, 62
	v_cndmask_b32_e64 v134, v134, v155, s[6:7]
	v_cndmask_b32_e64 v131, v135, v131, s[6:7]
	v_mul_f32_e32 v21, v21, v128
	v_mul_f32_e32 v23, v23, v129
	v_lshl_add_u64 v[128:129], s[22:23], 0, v[144:145]
	v_mul_f32_e32 v20, v20, v154
	v_mul_f32_e32 v22, v22, v132
	v_mul_f32_e32 v16, v16, v133
	v_mul_f32_e32 v17, v17, v130
	v_mul_f32_e32 v18, v18, v134
	v_mul_f32_e32 v19, v19, v131
	s_and_b64 vcc, exec, s[8:9]
	v_lshl_add_u64 v[144:145], v[140:141], 1, v[128:129]
	s_cbranch_vccnz .LBB0_370
	v_cvt_pk_bf16_f32 v128, v20, v21
	v_cvt_pk_bf16_f32 v129, v22, v23
	v_cvt_pk_bf16_f32 v130, v16, v17
	v_cvt_pk_bf16_f32 v131, v18, v19
	global_store_dwordx4 v[144:145], v[128:131], off
.LBB0_370:
	s_nop 1
	v_add_co_u32_e32 v128, vcc, 0x6000, v138
	s_nop 1
	v_addc_co_u32_e32 v129, vcc, 0, v139, vcc
	s_waitcnt vmcnt(14)
	v_mov_b64_e32 v[128:129], v[180:181]
	v_mov_b64_e32 v[130:131], v[182:183]
	s_and_b64 vcc, exec, s[10:11]
	v_mov_b64_e32 v[132:133], v[184:185]
	v_mov_b64_e32 v[134:135], v[186:187]
	v_add_co_u32_e32 v198, vcc, 0x16000, v138
	s_nop 1
	v_addc_co_u32_e32 v199, vcc, 0, v139, vcc
	global_load_dwordx4 v[180:183], v[198:199], off
	v_lshl_add_u64 v[198:199], v[198:199], 0, v[200:201]
	global_load_dwordx4 v[184:187], v[198:199], off
; __device__ __forceinline__ unsigned cvt_pk_bf16(float lo, float hi) { unsigned r; asm("v_cvt_pk_bf16_f32 %0, %1, %2" : "=v"(r) : "v"(lo), "v"(hi)); return r; }
; __device__ __forceinline__ float bf_lo(unsigned w) { return __uint_as_float(w << 16); }
; __device__ __forceinline__ float bf_hi(unsigned w) { return __uint_as_float(w & 0xffff0000u); }
;     __device__ __forceinline__ void operator()(f32x4 (&acc)[2][2][4][2], const Unit& u, int wr, int wc, int fr, int fq) const {
;     ...
;         for (int ai = 0; ai < 2; ++ai)
; #pragma unroll
;             for (int m = 0; m < 4; ++m) { const size_t row = (size_t)(row0 + ai * HALF + m * 16);
; #pragma unroll
;                 for (int bj = 0; bj < 2; ++bj) { const size_t so = (size_t)((ai * 4 + m) * 2 + bj) * 512;
;                     const u32x4 zn = gn[so]; u32x4 zd = zn; if (!fin) zd = gd[so];
;                     float f[8];
; #pragma unroll
;                     for (int q = 0; q < 4; ++q) { f[2 * q] = fin ? bf_lo(zn[q]) : bf_lo(zn[q]) * __builtin_amdgcn_rcpf(bf_lo(zd[q])); f[2 * q + 1] = fin ? bf_hi(zn[q]) : bf_hi(zn[q]) * __builtin_amdgcn_rcpf(bf_hi(zd[q])); }
;                     f32x4 v0 = acc[ai][bj][m][0], v1 = acc[ai][bj][m][1];
;                     v0[0] *= f[0]; v0[1] *= f[1]; v0[2] *= f[2]; v0[3] *= f[3]; v1[0] *= f[4]; v1[1] *= f[5]; v1[2] *= f[6]; v1[3] *= f[7];
;                     acc[ai][bj][m][0] = v0; acc[ai][bj][m][1] = v1;
;                     if (fin) { u32x4 w; w.x = cvt_pk_bf16(v0[0], v0[1]); w.y = cvt_pk_bf16(v0[2], v0[3]); w.z = cvt_pk_bf16(v1[0], v1[1]); w.w = cvt_pk_bf16(v1[2], v1[3]);
;                         *(u32x4*)(O + row * DM + col0 + bj * HALF) = w; } }
;                 if (m & 1) { asm volatile("" ::: "memory"); __builtin_amdgcn_sched_barrier(0); } }
.LBB0_372:
	v_lshlrev_b32_e32 v154, 16, v132
	v_and_b32_e32 v132, 0xffff0000, v132
	v_rcp_f32_e32 v132, v132
	v_lshlrev_b32_e32 v155, 16, v128
	v_and_b32_e32 v128, 0xffff0000, v128
	v_rcp_f32_e32 v154, v154
	v_mul_f32_e32 v132, v132, v128
	v_cndmask_b32_e64 v128, v132, v128, s[6:7]
	v_lshlrev_b32_e32 v132, 16, v133
	v_and_b32_e32 v133, 0xffff0000, v133
	v_rcp_f32_e32 v133, v133
	v_mul_f32_e32 v154, v154, v155
	v_cndmask_b32_e64 v154, v154, v155, s[6:7]
	v_lshlrev_b32_e32 v155, 16, v129
	v_and_b32_e32 v129, 0xffff0000, v129
	v_rcp_f32_e32 v132, v132
	v_mul_f32_e32 v133, v133, v129
	v_cndmask_b32_e64 v129, v133, v129, s[6:7]
	v_lshlrev_b32_e32 v133, 16, v134
	v_and_b32_e32 v134, 0xffff0000, v134
	v_rcp_f32_e32 v134, v134
	v_mul_f32_e32 v132, v132, v155
	v_cndmask_b32_e64 v132, v132, v155, s[6:7]
	v_lshlrev_b32_e32 v155, 16, v130
	v_and_b32_e32 v130, 0xffff0000, v130
	v_rcp_f32_e32 v133, v133
	v_mul_f32_e32 v134, v134, v130
	v_cndmask_b32_e64 v130, v134, v130, s[6:7]
	v_lshlrev_b32_e32 v134, 16, v135
	v_and_b32_e32 v135, 0xffff0000, v135
	v_rcp_f32_e32 v134, v134
	v_rcp_f32_e32 v135, v135
	v_mul_f32_e32 v133, v133, v155
	v_cndmask_b32_e64 v133, v133, v155, s[6:7]
	v_lshlrev_b32_e32 v155, 16, v131
	v_and_b32_e32 v131, 0xffff0000, v131
	v_mul_f32_e32 v134, v134, v155
	v_mul_f32_e32 v135, v135, v131
	v_cndmask_b32_e64 v134, v134, v155, s[6:7]
	v_cndmask_b32_e64 v131, v135, v131, s[6:7]
	v_mul_f32_e32 v28, v28, v154
	v_mul_f32_e32 v29, v29, v128
	v_mul_f32_e32 v30, v30, v132
	v_mul_f32_e32 v31, v31, v129
	v_mul_f32_e32 v24, v24, v133
	v_mul_f32_e32 v25, v25, v130
	v_mul_f32_e32 v26, v26, v134
	s_and_b64 vcc, exec, s[8:9]
	v_mul_f32_e32 v27, v27, v131
	s_cbranch_vccnz .LBB0_374
	v_cvt_pk_bf16_f32 v128, v28, v29
	v_cvt_pk_bf16_f32 v129, v30, v31
	v_cvt_pk_bf16_f32 v130, v24, v25
	v_cvt_pk_bf16_f32 v131, v26, v27
	global_store_dwordx4 v[144:145], v[128:131], off offset:256
.LBB0_374:
	s_nop 1
	v_add_co_u32_e32 v128, vcc, 0x8000, v138
	s_nop 1
	v_addc_co_u32_e32 v129, vcc, 0, v139, vcc
	s_waitcnt vmcnt(14)
	v_mov_b64_e32 v[128:129], v[226:227]
	v_mov_b64_e32 v[130:131], v[228:229]
	s_and_b64 vcc, exec, s[10:11]
	v_mov_b64_e32 v[132:133], v[230:231]
	v_mov_b64_e32 v[134:135], v[232:233]
	v_add_co_u32_e32 v198, vcc, 0x18000, v138
	s_nop 1
	v_addc_co_u32_e32 v199, vcc, 0, v139, vcc
	global_load_dwordx4 v[226:229], v[198:199], off
	v_lshl_add_u64 v[198:199], v[198:199], 0, v[200:201]
	global_load_dwordx4 v[230:233], v[198:199], off
.LBB0_376:
	v_lshlrev_b32_e32 v154, 16, v132
	v_and_b32_e32 v132, 0xffff0000, v132
	v_rcp_f32_e32 v132, v132
	v_lshlrev_b32_e32 v155, 16, v128
	v_and_b32_e32 v128, 0xffff0000, v128
	v_rcp_f32_e32 v154, v154
	v_mul_f32_e32 v132, v132, v128
	v_cndmask_b32_e64 v128, v132, v128, s[6:7]
	v_lshlrev_b32_e32 v132, 16, v133
	v_and_b32_e32 v133, 0xffff0000, v133
	v_rcp_f32_e32 v133, v133
	v_mul_f32_e32 v154, v154, v155
	v_cndmask_b32_e64 v154, v154, v155, s[6:7]
	v_lshlrev_b32_e32 v155, 16, v129
	v_and_b32_e32 v129, 0xffff0000, v129
	v_rcp_f32_e32 v132, v132
	v_mul_f32_e32 v133, v133, v129
	v_cndmask_b32_e64 v129, v133, v129, s[6:7]
	v_lshlrev_b32_e32 v133, 16, v134
	v_and_b32_e32 v134, 0xffff0000, v134
	v_rcp_f32_e32 v134, v134
	v_mul_f32_e32 v132, v132, v155
	v_cndmask_b32_e64 v132, v132, v155, s[6:7]
	v_lshlrev_b32_e32 v155, 16, v130
	v_and_b32_e32 v130, 0xffff0000, v130
	v_rcp_f32_e32 v133, v133
	v_mul_f32_e32 v134, v134, v130
	v_cndmask_b32_e64 v130, v134, v130, s[6:7]
	v_lshlrev_b32_e32 v134, 16, v135
	v_and_b32_e32 v135, 0xffff0000, v135
	v_rcp_f32_e32 v134, v134
	v_rcp_f32_e32 v135, v135
	v_or_b32_e32 v144, 32, v142
	v_mul_f32_e32 v133, v133, v155
	v_ashrrev_i32_e32 v145, 31, v144
	v_cndmask_b32_e64 v133, v133, v155, s[6:7]
	v_lshlrev_b32_e32 v155, 16, v131
	v_and_b32_e32 v131, 0xffff0000, v131
	v_readlane_b32 s22, v253, 61
	v_lshlrev_b64 v[144:145], 11, v[144:145]
	v_mul_f32_e32 v134, v134, v155
	v_mul_f32_e32 v135, v135, v131
	v_readlane_b32 s23, v253, 62
	v_cndmask_b32_e64 v134, v134, v155, s[6:7]
	v_cndmask_b32_e64 v131, v135, v131, s[6:7]
	v_mul_f32_e32 v37, v37, v128
	v_mul_f32_e32 v39, v39, v129
	v_lshl_add_u64 v[128:129], s[22:23], 0, v[144:145]
	v_mul_f32_e32 v36, v36, v154
	v_mul_f32_e32 v38, v38, v132
	v_mul_f32_e32 v32, v32, v133
	v_mul_f32_e32 v33, v33, v130
	v_mul_f32_e32 v34, v34, v134
	v_mul_f32_e32 v35, v35, v131
	s_and_b64 vcc, exec, s[8:9]
	v_lshl_add_u64 v[144:145], v[140:141], 1, v[128:129]
	s_cbranch_vccnz .LBB0_378
	v_cvt_pk_bf16_f32 v128, v36, v37
	v_cvt_pk_bf16_f32 v129, v38, v39
	v_cvt_pk_bf16_f32 v130, v32, v33
	v_cvt_pk_bf16_f32 v131, v34, v35
	global_store_dwordx4 v[144:145], v[128:131], off
.LBB0_378:
	s_nop 1
	v_add_co_u32_e32 v128, vcc, 0xa000, v138
	s_nop 1
	v_addc_co_u32_e32 v129, vcc, 0, v139, vcc
	s_waitcnt vmcnt(14)
	v_mov_b64_e32 v[128:129], v[234:235]
	v_mov_b64_e32 v[130:131], v[236:237]
	s_and_b64 vcc, exec, s[10:11]
	v_mov_b64_e32 v[132:133], v[238:239]
	v_mov_b64_e32 v[134:135], v[240:241]
	v_add_co_u32_e32 v198, vcc, 0x1a000, v138
	s_nop 1
	v_addc_co_u32_e32 v199, vcc, 0, v139, vcc
	global_load_dwordx4 v[234:237], v[198:199], off
	v_lshl_add_u64 v[198:199], v[198:199], 0, v[200:201]
	global_load_dwordx4 v[238:241], v[198:199], off
; __device__ __forceinline__ unsigned cvt_pk_bf16(float lo, float hi) { unsigned r; asm("v_cvt_pk_bf16_f32 %0, %1, %2" : "=v"(r) : "v"(lo), "v"(hi)); return r; }
; __device__ __forceinline__ float bf_lo(unsigned w) { return __uint_as_float(w << 16); }
; __device__ __forceinline__ float bf_hi(unsigned w) { return __uint_as_float(w & 0xffff0000u); }
;     __device__ __forceinline__ void operator()(f32x4 (&acc)[2][2][4][2], const Unit& u, int wr, int wc, int fr, int fq) const {
;     ...
;         for (int ai = 0; ai < 2; ++ai)
; #pragma unroll
;             for (int m = 0; m < 4; ++m) { const size_t row = (size_t)(row0 + ai * HALF + m * 16);
; #pragma unroll
;                 for (int bj = 0; bj < 2; ++bj) { const size_t so = (size_t)((ai * 4 + m) * 2 + bj) * 512;
;                     const u32x4 zn = gn[so]; u32x4 zd = zn; if (!fin) zd = gd[so];
;                     float f[8];
; #pragma unroll
;                     for (int q = 0; q < 4; ++q) { f[2 * q] = fin ? bf_lo(zn[q]) : bf_lo(zn[q]) * __builtin_amdgcn_rcpf(bf_lo(zd[q])); f[2 * q + 1] = fin ? bf_hi(zn[q]) : bf_hi(zn[q]) * __builtin_amdgcn_rcpf(bf_hi(zd[q])); }
;                     f32x4 v0 = acc[ai][bj][m][0], v1 = acc[ai][bj][m][1];
;                     v0[0] *= f[0]; v0[1] *= f[1]; v0[2] *= f[2]; v0[3] *= f[3]; v1[0] *= f[4]; v1[1] *= f[5]; v1[2] *= f[6]; v1[3] *= f[7];
;                     acc[ai][bj][m][0] = v0; acc[ai][bj][m][1] = v1;
;                     if (fin) { u32x4 w; w.x = cvt_pk_bf16(v0[0], v0[1]); w.y = cvt_pk_bf16(v0[2], v0[3]); w.z = cvt_pk_bf16(v1[0], v1[1]); w.w = cvt_pk_bf16(v1[2], v1[3]);
;                         *(u32x4*)(O + row * DM + col0 + bj * HALF) = w; } }
;                 if (m & 1) { asm volatile("" ::: "memory"); __builtin_amdgcn_sched_barrier(0); } }
.LBB0_380:
	v_lshlrev_b32_e32 v154, 16, v132
	v_and_b32_e32 v132, 0xffff0000, v132
	v_rcp_f32_e32 v132, v132
	v_lshlrev_b32_e32 v155, 16, v128
	v_and_b32_e32 v128, 0xffff0000, v128
	v_rcp_f32_e32 v154, v154
	v_mul_f32_e32 v132, v132, v128
	v_cndmask_b32_e64 v128, v132, v128, s[6:7]
	v_lshlrev_b32_e32 v132, 16, v133
	v_and_b32_e32 v133, 0xffff0000, v133
	v_rcp_f32_e32 v133, v133
	v_mul_f32_e32 v154, v154, v155
	v_cndmask_b32_e64 v154, v154, v155, s[6:7]
	v_lshlrev_b32_e32 v155, 16, v129
	v_and_b32_e32 v129, 0xffff0000, v129
	v_rcp_f32_e32 v132, v132
	v_mul_f32_e32 v133, v133, v129
	v_cndmask_b32_e64 v129, v133, v129, s[6:7]
	v_lshlrev_b32_e32 v133, 16, v134
	v_and_b32_e32 v134, 0xffff0000, v134
	v_rcp_f32_e32 v134, v134
	v_mul_f32_e32 v132, v132, v155
	v_cndmask_b32_e64 v132, v132, v155, s[6:7]
	v_lshlrev_b32_e32 v155, 16, v130
	v_and_b32_e32 v130, 0xffff0000, v130
	v_rcp_f32_e32 v133, v133
	v_mul_f32_e32 v134, v134, v130
	v_cndmask_b32_e64 v130, v134, v130, s[6:7]
	v_lshlrev_b32_e32 v134, 16, v135
	v_and_b32_e32 v135, 0xffff0000, v135
	v_rcp_f32_e32 v134, v134
	v_rcp_f32_e32 v135, v135
	v_mul_f32_e32 v133, v133, v155
	v_cndmask_b32_e64 v133, v133, v155, s[6:7]
	v_lshlrev_b32_e32 v155, 16, v131
	v_and_b32_e32 v131, 0xffff0000, v131
	v_mul_f32_e32 v134, v134, v155
	v_mul_f32_e32 v135, v135, v131
	v_cndmask_b32_e64 v134, v134, v155, s[6:7]
	v_cndmask_b32_e64 v131, v135, v131, s[6:7]
	v_mul_f32_e32 v44, v44, v154
	v_mul_f32_e32 v45, v45, v128
	v_mul_f32_e32 v46, v46, v132
	v_mul_f32_e32 v47, v47, v129
	v_mul_f32_e32 v40, v40, v133
	v_mul_f32_e32 v41, v41, v130
	v_mul_f32_e32 v42, v42, v134
	s_and_b64 vcc, exec, s[8:9]
	v_mul_f32_e32 v43, v43, v131
	s_cbranch_vccnz .LBB0_382
	v_cvt_pk_bf16_f32 v128, v44, v45
	v_cvt_pk_bf16_f32 v129, v46, v47
	v_cvt_pk_bf16_f32 v130, v40, v41
	v_cvt_pk_bf16_f32 v131, v42, v43
	global_store_dwordx4 v[144:145], v[128:131], off offset:256
.LBB0_382:
	s_nop 1
	v_add_co_u32_e32 v128, vcc, 0xc000, v138
	s_nop 1
	v_addc_co_u32_e32 v129, vcc, 0, v139, vcc
	s_waitcnt vmcnt(14)
	v_mov_b64_e32 v[128:129], v[242:243]
	v_mov_b64_e32 v[130:131], v[244:245]
	s_and_b64 vcc, exec, s[10:11]
	v_mov_b64_e32 v[132:133], v[246:247]
	v_mov_b64_e32 v[134:135], v[248:249]
	v_add_co_u32_e32 v198, vcc, 0x1c000, v138
	s_nop 1
	v_addc_co_u32_e32 v199, vcc, 0, v139, vcc
	global_load_dwordx4 v[242:245], v[198:199], off
	v_lshl_add_u64 v[198:199], v[198:199], 0, v[200:201]
	global_load_dwordx4 v[246:249], v[198:199], off
.LBB0_384:
	v_lshlrev_b32_e32 v154, 16, v132
	v_and_b32_e32 v132, 0xffff0000, v132
	v_rcp_f32_e32 v132, v132
	v_lshlrev_b32_e32 v155, 16, v128
	v_and_b32_e32 v128, 0xffff0000, v128
	v_rcp_f32_e32 v154, v154
	v_mul_f32_e32 v132, v132, v128
	v_cndmask_b32_e64 v128, v132, v128, s[6:7]
	v_lshlrev_b32_e32 v132, 16, v133
	v_and_b32_e32 v133, 0xffff0000, v133
	v_rcp_f32_e32 v133, v133
	v_mul_f32_e32 v154, v154, v155
	v_cndmask_b32_e64 v154, v154, v155, s[6:7]
	v_lshlrev_b32_e32 v155, 16, v129
	v_and_b32_e32 v129, 0xffff0000, v129
	v_rcp_f32_e32 v132, v132
	v_mul_f32_e32 v133, v133, v129
	v_cndmask_b32_e64 v129, v133, v129, s[6:7]
	v_lshlrev_b32_e32 v133, 16, v134
	v_and_b32_e32 v134, 0xffff0000, v134
	v_rcp_f32_e32 v134, v134
	v_mul_f32_e32 v132, v132, v155
	v_cndmask_b32_e64 v132, v132, v155, s[6:7]
	v_lshlrev_b32_e32 v155, 16, v130
	v_and_b32_e32 v130, 0xffff0000, v130
	v_rcp_f32_e32 v133, v133
	v_mul_f32_e32 v134, v134, v130
	v_cndmask_b32_e64 v130, v134, v130, s[6:7]
	v_lshlrev_b32_e32 v134, 16, v135
	v_and_b32_e32 v135, 0xffff0000, v135
	v_rcp_f32_e32 v134, v134
	v_rcp_f32_e32 v135, v135
	v_or_b32_e32 v144, 48, v142
	v_mul_f32_e32 v133, v133, v155
	v_ashrrev_i32_e32 v145, 31, v144
	v_cndmask_b32_e64 v133, v133, v155, s[6:7]
	v_lshlrev_b32_e32 v155, 16, v131
	v_and_b32_e32 v131, 0xffff0000, v131
	v_readlane_b32 s22, v253, 61
	v_lshlrev_b64 v[144:145], 11, v[144:145]
	v_mul_f32_e32 v134, v134, v155
	v_mul_f32_e32 v135, v135, v131
	v_readlane_b32 s23, v253, 62
	v_cndmask_b32_e64 v134, v134, v155, s[6:7]
	v_cndmask_b32_e64 v131, v135, v131, s[6:7]
	v_mul_f32_e32 v53, v53, v128
	v_mul_f32_e32 v55, v55, v129
	v_lshl_add_u64 v[128:129], s[22:23], 0, v[144:145]
	v_mul_f32_e32 v52, v52, v154
	v_mul_f32_e32 v54, v54, v132
	v_mul_f32_e32 v48, v48, v133
	v_mul_f32_e32 v49, v49, v130
	v_mul_f32_e32 v50, v50, v134
	v_mul_f32_e32 v51, v51, v131
	s_and_b64 vcc, exec, s[8:9]
	v_lshl_add_u64 v[144:145], v[140:141], 1, v[128:129]
	s_cbranch_vccnz .LBB0_386
	v_cvt_pk_bf16_f32 v128, v52, v53
	v_cvt_pk_bf16_f32 v129, v54, v55
	v_cvt_pk_bf16_f32 v130, v48, v49
	v_cvt_pk_bf16_f32 v131, v50, v51
	global_store_dwordx4 v[144:145], v[128:131], off
.LBB0_386:
	s_nop 1
	v_add_co_u32_e32 v128, vcc, 0xe000, v138
	s_nop 1
	v_addc_co_u32_e32 v129, vcc, 0, v139, vcc
	s_waitcnt vmcnt(14)
	v_mov_b64_e32 v[128:129], v[202:203]
	v_mov_b64_e32 v[130:131], v[204:205]
	s_and_b64 vcc, exec, s[10:11]
	v_mov_b64_e32 v[132:133], v[194:195]
	v_mov_b64_e32 v[134:135], v[196:197]
	v_add_co_u32_e32 v198, vcc, 0x1e000, v138
	s_nop 1
	v_addc_co_u32_e32 v199, vcc, 0, v139, vcc
	global_load_dwordx4 v[202:205], v[198:199], off
	v_lshl_add_u64 v[198:199], v[198:199], 0, v[200:201]
	global_load_dwordx4 v[194:197], v[198:199], off
; __device__ __forceinline__ unsigned cvt_pk_bf16(float lo, float hi) { unsigned r; asm("v_cvt_pk_bf16_f32 %0, %1, %2" : "=v"(r) : "v"(lo), "v"(hi)); return r; }
; __device__ __forceinline__ float bf_lo(unsigned w) { return __uint_as_float(w << 16); }
; __device__ __forceinline__ float bf_hi(unsigned w) { return __uint_as_float(w & 0xffff0000u); }
;     __device__ __forceinline__ void operator()(f32x4 (&acc)[2][2][4][2], const Unit& u, int wr, int wc, int fr, int fq) const {
;     ...
;         for (int ai = 0; ai < 2; ++ai)
; #pragma unroll
;             for (int m = 0; m < 4; ++m) { const size_t row = (size_t)(row0 + ai * HALF + m * 16);
; #pragma unroll
;                 for (int bj = 0; bj < 2; ++bj) { const size_t so = (size_t)((ai * 4 + m) * 2 + bj) * 512;
;                     const u32x4 zn = gn[so]; u32x4 zd = zn; if (!fin) zd = gd[so];
;                     float f[8];
; #pragma unroll
;                     for (int q = 0; q < 4; ++q) { f[2 * q] = fin ? bf_lo(zn[q]) : bf_lo(zn[q]) * __builtin_amdgcn_rcpf(bf_lo(zd[q])); f[2 * q + 1] = fin ? bf_hi(zn[q]) : bf_hi(zn[q]) * __builtin_amdgcn_rcpf(bf_hi(zd[q])); }
;                     f32x4 v0 = acc[ai][bj][m][0], v1 = acc[ai][bj][m][1];
;                     v0[0] *= f[0]; v0[1] *= f[1]; v0[2] *= f[2]; v0[3] *= f[3]; v1[0] *= f[4]; v1[1] *= f[5]; v1[2] *= f[6]; v1[3] *= f[7];
;                     acc[ai][bj][m][0] = v0; acc[ai][bj][m][1] = v1;
;                     if (fin) { u32x4 w; w.x = cvt_pk_bf16(v0[0], v0[1]); w.y = cvt_pk_bf16(v0[2], v0[3]); w.z = cvt_pk_bf16(v1[0], v1[1]); w.w = cvt_pk_bf16(v1[2], v1[3]);
;                         *(u32x4*)(O + row * DM + col0 + bj * HALF) = w; } }
;                 if (m & 1) { asm volatile("" ::: "memory"); __builtin_amdgcn_sched_barrier(0); } }
.LBB0_388:
	v_lshlrev_b32_e32 v154, 16, v132
	v_and_b32_e32 v132, 0xffff0000, v132
	v_rcp_f32_e32 v132, v132
	v_lshlrev_b32_e32 v155, 16, v128
	v_and_b32_e32 v128, 0xffff0000, v128
	v_rcp_f32_e32 v154, v154
	v_mul_f32_e32 v132, v132, v128
	v_cndmask_b32_e64 v128, v132, v128, s[6:7]
	v_lshlrev_b32_e32 v132, 16, v133
	v_and_b32_e32 v133, 0xffff0000, v133
	v_rcp_f32_e32 v133, v133
	v_mul_f32_e32 v154, v154, v155
	v_cndmask_b32_e64 v154, v154, v155, s[6:7]
	v_lshlrev_b32_e32 v155, 16, v129
	v_and_b32_e32 v129, 0xffff0000, v129
	v_rcp_f32_e32 v132, v132
	v_mul_f32_e32 v133, v133, v129
	v_cndmask_b32_e64 v129, v133, v129, s[6:7]
	v_lshlrev_b32_e32 v133, 16, v134
	v_and_b32_e32 v134, 0xffff0000, v134
	v_rcp_f32_e32 v134, v134
	v_mul_f32_e32 v132, v132, v155
	v_cndmask_b32_e64 v132, v132, v155, s[6:7]
	v_lshlrev_b32_e32 v155, 16, v130
	v_and_b32_e32 v130, 0xffff0000, v130
	v_rcp_f32_e32 v133, v133
	v_mul_f32_e32 v134, v134, v130
	v_cndmask_b32_e64 v130, v134, v130, s[6:7]
	v_lshlrev_b32_e32 v134, 16, v135
	v_and_b32_e32 v135, 0xffff0000, v135
	v_rcp_f32_e32 v134, v134
	v_rcp_f32_e32 v135, v135
	v_mul_f32_e32 v133, v133, v155
	v_cndmask_b32_e64 v133, v133, v155, s[6:7]
	v_lshlrev_b32_e32 v155, 16, v131
	v_and_b32_e32 v131, 0xffff0000, v131
	v_mul_f32_e32 v134, v134, v155
	v_mul_f32_e32 v135, v135, v131
	v_cndmask_b32_e64 v134, v134, v155, s[6:7]
	v_cndmask_b32_e64 v131, v135, v131, s[6:7]
	v_mul_f32_e32 v60, v60, v154
	v_mul_f32_e32 v61, v61, v128
	v_mul_f32_e32 v62, v62, v132
	v_mul_f32_e32 v63, v63, v129
	v_mul_f32_e32 v56, v56, v133
	v_mul_f32_e32 v57, v57, v130
	v_mul_f32_e32 v58, v58, v134
	s_and_b64 vcc, exec, s[8:9]
	v_mul_f32_e32 v59, v59, v131
	s_cbranch_vccnz .LBB0_390
	v_cvt_pk_bf16_f32 v128, v60, v61
	v_cvt_pk_bf16_f32 v129, v62, v63
	v_cvt_pk_bf16_f32 v130, v56, v57
	v_cvt_pk_bf16_f32 v131, v58, v59
	global_store_dwordx4 v[144:145], v[128:131], off offset:256
.LBB0_390:
	s_nop 1
	v_add_co_u32_e32 v128, vcc, 0x10000, v138
	s_nop 1
	v_addc_co_u32_e32 v129, vcc, 0, v139, vcc
	s_waitcnt vmcnt(14)
	v_mov_b64_e32 v[128:129], v[156:157]
	v_mov_b64_e32 v[130:131], v[158:159]
	s_and_b64 vcc, exec, s[10:11]
	v_mov_b64_e32 v[132:133], v[160:161]
	v_mov_b64_e32 v[134:135], v[162:163]
.LBB0_392:
	v_lshlrev_b32_e32 v154, 16, v132
	v_and_b32_e32 v132, 0xffff0000, v132
	v_rcp_f32_e32 v132, v132
	v_lshlrev_b32_e32 v155, 16, v128
	v_and_b32_e32 v128, 0xffff0000, v128
	v_rcp_f32_e32 v154, v154
	v_mul_f32_e32 v132, v132, v128
	v_cndmask_b32_e64 v128, v132, v128, s[6:7]
	v_lshlrev_b32_e32 v132, 16, v133
	v_and_b32_e32 v133, 0xffff0000, v133
	v_rcp_f32_e32 v133, v133
	v_mul_f32_e32 v154, v154, v155
	v_cndmask_b32_e64 v154, v154, v155, s[6:7]
	v_lshlrev_b32_e32 v155, 16, v129
	v_and_b32_e32 v129, 0xffff0000, v129
	v_rcp_f32_e32 v132, v132
	v_mul_f32_e32 v133, v133, v129
	v_cndmask_b32_e64 v129, v133, v129, s[6:7]
	v_lshlrev_b32_e32 v133, 16, v134
	v_and_b32_e32 v134, 0xffff0000, v134
	v_rcp_f32_e32 v134, v134
	v_mul_f32_e32 v132, v132, v155
	v_cndmask_b32_e64 v132, v132, v155, s[6:7]
	v_lshlrev_b32_e32 v155, 16, v130
	v_and_b32_e32 v130, 0xffff0000, v130
	v_rcp_f32_e32 v133, v133
	v_mul_f32_e32 v134, v134, v130
	v_cndmask_b32_e64 v130, v134, v130, s[6:7]
	v_lshlrev_b32_e32 v134, 16, v135
	v_and_b32_e32 v135, 0xffff0000, v135
	v_rcp_f32_e32 v134, v134
	v_rcp_f32_e32 v135, v135
	v_lshlrev_b64 v[144:145], 11, v[142:143]
	s_mov_b64 s[22:23], 0x40000
	v_mul_f32_e32 v133, v133, v155
	v_lshl_add_u64 v[144:145], v[144:145], 0, s[22:23]
	v_cndmask_b32_e64 v133, v133, v155, s[6:7]
	v_lshlrev_b32_e32 v155, 16, v131
	v_and_b32_e32 v131, 0xffff0000, v131
	v_readlane_b32 s22, v253, 61
	v_mul_f32_e32 v134, v134, v155
	v_mul_f32_e32 v135, v135, v131
	v_readlane_b32 s23, v253, 62
	v_cndmask_b32_e64 v134, v134, v155, s[6:7]
	v_cndmask_b32_e64 v131, v135, v131, s[6:7]
	v_mul_f32_e32 v69, v69, v128
	v_mul_f32_e32 v71, v71, v129
	v_lshl_add_u64 v[128:129], s[22:23], 0, v[144:145]
	v_mul_f32_e32 v68, v68, v154
	v_mul_f32_e32 v70, v70, v132
	v_mul_f32_e32 v64, v64, v133
	v_mul_f32_e32 v65, v65, v130
	v_mul_f32_e32 v66, v66, v134
	v_mul_f32_e32 v67, v67, v131
	s_and_b64 vcc, exec, s[8:9]
	v_lshl_add_u64 v[144:145], v[140:141], 1, v[128:129]
	s_cbranch_vccnz .LBB0_394
	v_cvt_pk_bf16_f32 v128, v68, v69
	v_cvt_pk_bf16_f32 v129, v70, v71
	v_cvt_pk_bf16_f32 v130, v64, v65
	v_cvt_pk_bf16_f32 v131, v66, v67
	global_store_dwordx4 v[144:145], v[128:131], off
.LBB0_394:
	s_nop 1
	v_add_co_u32_e32 v128, vcc, 0x12000, v138
	s_nop 1
	v_addc_co_u32_e32 v129, vcc, 0, v139, vcc
	s_waitcnt vmcnt(12)
	v_mov_b64_e32 v[128:129], v[164:165]
	v_mov_b64_e32 v[130:131], v[166:167]
	s_and_b64 vcc, exec, s[10:11]
	v_mov_b64_e32 v[132:133], v[168:169]
	v_mov_b64_e32 v[134:135], v[170:171]
; __device__ __forceinline__ unsigned cvt_pk_bf16(float lo, float hi) { unsigned r; asm("v_cvt_pk_bf16_f32 %0, %1, %2" : "=v"(r) : "v"(lo), "v"(hi)); return r; }
; __device__ __forceinline__ float bf_lo(unsigned w) { return __uint_as_float(w << 16); }
; __device__ __forceinline__ float bf_hi(unsigned w) { return __uint_as_float(w & 0xffff0000u); }
;     __device__ __forceinline__ void operator()(f32x4 (&acc)[2][2][4][2], const Unit& u, int wr, int wc, int fr, int fq) const {
;     ...
;         for (int ai = 0; ai < 2; ++ai)
; #pragma unroll
;             for (int m = 0; m < 4; ++m) { const size_t row = (size_t)(row0 + ai * HALF + m * 16);
; #pragma unroll
;                 for (int bj = 0; bj < 2; ++bj) { const size_t so = (size_t)((ai * 4 + m) * 2 + bj) * 512;
;                     const u32x4 zn = gn[so]; u32x4 zd = zn; if (!fin) zd = gd[so];
;                     float f[8];
; #pragma unroll
;                     for (int q = 0; q < 4; ++q) { f[2 * q] = fin ? bf_lo(zn[q]) : bf_lo(zn[q]) * __builtin_amdgcn_rcpf(bf_lo(zd[q])); f[2 * q + 1] = fin ? bf_hi(zn[q]) : bf_hi(zn[q]) * __builtin_amdgcn_rcpf(bf_hi(zd[q])); }
;                     f32x4 v0 = acc[ai][bj][m][0], v1 = acc[ai][bj][m][1];
;                     v0[0] *= f[0]; v0[1] *= f[1]; v0[2] *= f[2]; v0[3] *= f[3]; v1[0] *= f[4]; v1[1] *= f[5]; v1[2] *= f[6]; v1[3] *= f[7];
;                     acc[ai][bj][m][0] = v0; acc[ai][bj][m][1] = v1;
;                     if (fin) { u32x4 w; w.x = cvt_pk_bf16(v0[0], v0[1]); w.y = cvt_pk_bf16(v0[2], v0[3]); w.z = cvt_pk_bf16(v1[0], v1[1]); w.w = cvt_pk_bf16(v1[2], v1[3]);
;                         *(u32x4*)(O + row * DM + col0 + bj * HALF) = w; } }
;                 if (m & 1) { asm volatile("" ::: "memory"); __builtin_amdgcn_sched_barrier(0); } }
.LBB0_396:
	v_lshlrev_b32_e32 v154, 16, v132
	v_and_b32_e32 v132, 0xffff0000, v132
	v_rcp_f32_e32 v132, v132
	v_lshlrev_b32_e32 v155, 16, v128
	v_and_b32_e32 v128, 0xffff0000, v128
	v_rcp_f32_e32 v154, v154
	v_mul_f32_e32 v132, v132, v128
	v_cndmask_b32_e64 v128, v132, v128, s[6:7]
	v_lshlrev_b32_e32 v132, 16, v133
	v_and_b32_e32 v133, 0xffff0000, v133
	v_rcp_f32_e32 v133, v133
	v_mul_f32_e32 v154, v154, v155
	v_cndmask_b32_e64 v154, v154, v155, s[6:7]
	v_lshlrev_b32_e32 v155, 16, v129
	v_and_b32_e32 v129, 0xffff0000, v129
	v_rcp_f32_e32 v132, v132
	v_mul_f32_e32 v133, v133, v129
	v_cndmask_b32_e64 v129, v133, v129, s[6:7]
	v_lshlrev_b32_e32 v133, 16, v134
	v_and_b32_e32 v134, 0xffff0000, v134
	v_rcp_f32_e32 v134, v134
	v_mul_f32_e32 v132, v132, v155
	v_cndmask_b32_e64 v132, v132, v155, s[6:7]
	v_lshlrev_b32_e32 v155, 16, v130
	v_and_b32_e32 v130, 0xffff0000, v130
	v_rcp_f32_e32 v133, v133
	v_mul_f32_e32 v134, v134, v130
	v_cndmask_b32_e64 v130, v134, v130, s[6:7]
	v_lshlrev_b32_e32 v134, 16, v135
	v_and_b32_e32 v135, 0xffff0000, v135
	v_rcp_f32_e32 v134, v134
	v_rcp_f32_e32 v135, v135
	v_mul_f32_e32 v133, v133, v155
	v_cndmask_b32_e64 v133, v133, v155, s[6:7]
	v_lshlrev_b32_e32 v155, 16, v131
	v_and_b32_e32 v131, 0xffff0000, v131
	v_mul_f32_e32 v134, v134, v155
	v_mul_f32_e32 v135, v135, v131
	v_cndmask_b32_e64 v134, v134, v155, s[6:7]
	v_cndmask_b32_e64 v131, v135, v131, s[6:7]
	v_mul_f32_e32 v76, v76, v154
	v_mul_f32_e32 v77, v77, v128
	v_mul_f32_e32 v78, v78, v132
	v_mul_f32_e32 v79, v79, v129
	v_mul_f32_e32 v72, v72, v133
	v_mul_f32_e32 v73, v73, v130
	v_mul_f32_e32 v74, v74, v134
	s_and_b64 vcc, exec, s[8:9]
	v_mul_f32_e32 v75, v75, v131
	s_cbranch_vccnz .LBB0_398
	v_cvt_pk_bf16_f32 v128, v76, v77
	v_cvt_pk_bf16_f32 v129, v78, v79
	v_cvt_pk_bf16_f32 v130, v72, v73
	v_cvt_pk_bf16_f32 v131, v74, v75
	global_store_dwordx4 v[144:145], v[128:131], off offset:256
.LBB0_398:
	s_nop 1
	v_add_co_u32_e32 v128, vcc, 0x14000, v138
	s_nop 1
	v_addc_co_u32_e32 v129, vcc, 0, v139, vcc
	s_waitcnt vmcnt(10)
	v_mov_b64_e32 v[128:129], v[172:173]
	v_mov_b64_e32 v[130:131], v[174:175]
	s_and_b64 vcc, exec, s[10:11]
	v_mov_b64_e32 v[132:133], v[176:177]
	v_mov_b64_e32 v[134:135], v[178:179]
.LBB0_400:
	v_lshlrev_b32_e32 v154, 16, v132
	v_and_b32_e32 v132, 0xffff0000, v132
	v_rcp_f32_e32 v132, v132
	v_lshlrev_b32_e32 v155, 16, v128
	v_and_b32_e32 v128, 0xffff0000, v128
	v_rcp_f32_e32 v154, v154
	v_mul_f32_e32 v132, v132, v128
	v_cndmask_b32_e64 v128, v132, v128, s[6:7]
	v_lshlrev_b32_e32 v132, 16, v133
	v_and_b32_e32 v133, 0xffff0000, v133
	v_rcp_f32_e32 v133, v133
	v_mul_f32_e32 v154, v154, v155
	v_cndmask_b32_e64 v154, v154, v155, s[6:7]
	v_lshlrev_b32_e32 v155, 16, v129
	v_and_b32_e32 v129, 0xffff0000, v129
	v_rcp_f32_e32 v132, v132
	v_mul_f32_e32 v133, v133, v129
	v_cndmask_b32_e64 v129, v133, v129, s[6:7]
	v_lshlrev_b32_e32 v133, 16, v134
	v_and_b32_e32 v134, 0xffff0000, v134
	v_rcp_f32_e32 v134, v134
	v_mul_f32_e32 v132, v132, v155
	v_cndmask_b32_e64 v132, v132, v155, s[6:7]
	v_lshlrev_b32_e32 v155, 16, v130
	v_and_b32_e32 v130, 0xffff0000, v130
	v_rcp_f32_e32 v133, v133
	v_mul_f32_e32 v134, v134, v130
	v_cndmask_b32_e64 v130, v134, v130, s[6:7]
	v_lshlrev_b32_e32 v134, 16, v135
	v_and_b32_e32 v135, 0xffff0000, v135
	v_rcp_f32_e32 v134, v134
	v_rcp_f32_e32 v135, v135
	v_lshlrev_b64 v[144:145], 11, v[142:143]
	s_mov_b64 s[22:23], 0x48000
	v_mul_f32_e32 v133, v133, v155
	v_lshl_add_u64 v[144:145], v[144:145], 0, s[22:23]
	v_cndmask_b32_e64 v133, v133, v155, s[6:7]
	v_lshlrev_b32_e32 v155, 16, v131
	v_and_b32_e32 v131, 0xffff0000, v131
	v_readlane_b32 s22, v253, 61
	v_mul_f32_e32 v134, v134, v155
	v_mul_f32_e32 v135, v135, v131
	v_readlane_b32 s23, v253, 62
	v_cndmask_b32_e64 v134, v134, v155, s[6:7]
	v_cndmask_b32_e64 v131, v135, v131, s[6:7]
	v_mul_f32_e32 v85, v85, v128
	v_mul_f32_e32 v87, v87, v129
	v_lshl_add_u64 v[128:129], s[22:23], 0, v[144:145]
	v_mul_f32_e32 v84, v84, v154
	v_mul_f32_e32 v86, v86, v132
	v_mul_f32_e32 v80, v80, v133
	v_mul_f32_e32 v81, v81, v130
	v_mul_f32_e32 v82, v82, v134
	v_mul_f32_e32 v83, v83, v131
	s_and_b64 vcc, exec, s[8:9]
	v_lshl_add_u64 v[144:145], v[140:141], 1, v[128:129]
	s_cbranch_vccnz .LBB0_402
	v_cvt_pk_bf16_f32 v128, v84, v85
	v_cvt_pk_bf16_f32 v129, v86, v87
	v_cvt_pk_bf16_f32 v130, v80, v81
	v_cvt_pk_bf16_f32 v131, v82, v83
	global_store_dwordx4 v[144:145], v[128:131], off
.LBB0_402:
	s_nop 1
	v_add_co_u32_e32 v128, vcc, 0x16000, v138
	s_nop 1
	v_addc_co_u32_e32 v129, vcc, 0, v139, vcc
	s_waitcnt vmcnt(8)
	v_mov_b64_e32 v[128:129], v[180:181]
	v_mov_b64_e32 v[130:131], v[182:183]
	s_and_b64 vcc, exec, s[10:11]
	v_mov_b64_e32 v[132:133], v[184:185]
	v_mov_b64_e32 v[134:135], v[186:187]
; __device__ __forceinline__ unsigned cvt_pk_bf16(float lo, float hi) { unsigned r; asm("v_cvt_pk_bf16_f32 %0, %1, %2" : "=v"(r) : "v"(lo), "v"(hi)); return r; }
; __device__ __forceinline__ float bf_lo(unsigned w) { return __uint_as_float(w << 16); }
; __device__ __forceinline__ float bf_hi(unsigned w) { return __uint_as_float(w & 0xffff0000u); }
;     __device__ __forceinline__ void operator()(f32x4 (&acc)[2][2][4][2], const Unit& u, int wr, int wc, int fr, int fq) const {
;     ...
;         for (int ai = 0; ai < 2; ++ai)
; #pragma unroll
;             for (int m = 0; m < 4; ++m) { const size_t row = (size_t)(row0 + ai * HALF + m * 16);
; #pragma unroll
;                 for (int bj = 0; bj < 2; ++bj) { const size_t so = (size_t)((ai * 4 + m) * 2 + bj) * 512;
;                     const u32x4 zn = gn[so]; u32x4 zd = zn; if (!fin) zd = gd[so];
;                     float f[8];
; #pragma unroll
;                     for (int q = 0; q < 4; ++q) { f[2 * q] = fin ? bf_lo(zn[q]) : bf_lo(zn[q]) * __builtin_amdgcn_rcpf(bf_lo(zd[q])); f[2 * q + 1] = fin ? bf_hi(zn[q]) : bf_hi(zn[q]) * __builtin_amdgcn_rcpf(bf_hi(zd[q])); }
;                     f32x4 v0 = acc[ai][bj][m][0], v1 = acc[ai][bj][m][1];
;                     v0[0] *= f[0]; v0[1] *= f[1]; v0[2] *= f[2]; v0[3] *= f[3]; v1[0] *= f[4]; v1[1] *= f[5]; v1[2] *= f[6]; v1[3] *= f[7];
;                     acc[ai][bj][m][0] = v0; acc[ai][bj][m][1] = v1;
;                     if (fin) { u32x4 w; w.x = cvt_pk_bf16(v0[0], v0[1]); w.y = cvt_pk_bf16(v0[2], v0[3]); w.z = cvt_pk_bf16(v1[0], v1[1]); w.w = cvt_pk_bf16(v1[2], v1[3]);
;                         *(u32x4*)(O + row * DM + col0 + bj * HALF) = w; } }
;                 if (m & 1) { asm volatile("" ::: "memory"); __builtin_amdgcn_sched_barrier(0); } }
.LBB0_404:
	v_lshlrev_b32_e32 v154, 16, v132
	v_and_b32_e32 v132, 0xffff0000, v132
	v_rcp_f32_e32 v132, v132
	v_lshlrev_b32_e32 v155, 16, v128
	v_and_b32_e32 v128, 0xffff0000, v128
	v_rcp_f32_e32 v154, v154
	v_mul_f32_e32 v132, v132, v128
	v_cndmask_b32_e64 v128, v132, v128, s[6:7]
	v_lshlrev_b32_e32 v132, 16, v133
	v_and_b32_e32 v133, 0xffff0000, v133
	v_rcp_f32_e32 v133, v133
	v_mul_f32_e32 v154, v154, v155
	v_cndmask_b32_e64 v154, v154, v155, s[6:7]
	v_lshlrev_b32_e32 v155, 16, v129
	v_and_b32_e32 v129, 0xffff0000, v129
	v_rcp_f32_e32 v132, v132
	v_mul_f32_e32 v133, v133, v129
	v_cndmask_b32_e64 v129, v133, v129, s[6:7]
	v_lshlrev_b32_e32 v133, 16, v134
	v_and_b32_e32 v134, 0xffff0000, v134
	v_rcp_f32_e32 v134, v134
	v_mul_f32_e32 v132, v132, v155
	v_cndmask_b32_e64 v132, v132, v155, s[6:7]
	v_lshlrev_b32_e32 v155, 16, v130
	v_and_b32_e32 v130, 0xffff0000, v130
	v_rcp_f32_e32 v133, v133
	v_mul_f32_e32 v134, v134, v130
	v_cndmask_b32_e64 v130, v134, v130, s[6:7]
	v_lshlrev_b32_e32 v134, 16, v135
	v_and_b32_e32 v135, 0xffff0000, v135
	v_rcp_f32_e32 v134, v134
	v_rcp_f32_e32 v135, v135
	v_mul_f32_e32 v133, v133, v155
	v_cndmask_b32_e64 v133, v133, v155, s[6:7]
	v_lshlrev_b32_e32 v155, 16, v131
	v_and_b32_e32 v131, 0xffff0000, v131
	v_mul_f32_e32 v134, v134, v155
	v_mul_f32_e32 v135, v135, v131
	v_cndmask_b32_e64 v134, v134, v155, s[6:7]
	v_cndmask_b32_e64 v131, v135, v131, s[6:7]
	v_mul_f32_e32 v92, v92, v154
	v_mul_f32_e32 v93, v93, v128
	v_mul_f32_e32 v94, v94, v132
	v_mul_f32_e32 v95, v95, v129
	v_mul_f32_e32 v88, v88, v133
	v_mul_f32_e32 v89, v89, v130
	v_mul_f32_e32 v90, v90, v134
	s_and_b64 vcc, exec, s[8:9]
	v_mul_f32_e32 v91, v91, v131
	s_cbranch_vccnz .LBB0_406
	v_cvt_pk_bf16_f32 v128, v92, v93
	v_cvt_pk_bf16_f32 v129, v94, v95
	v_cvt_pk_bf16_f32 v130, v88, v89
	v_cvt_pk_bf16_f32 v131, v90, v91
	global_store_dwordx4 v[144:145], v[128:131], off offset:256
.LBB0_406:
	s_nop 1
	v_add_co_u32_e32 v128, vcc, 0x18000, v138
	s_nop 1
	v_addc_co_u32_e32 v129, vcc, 0, v139, vcc
	s_waitcnt vmcnt(6)
	v_mov_b64_e32 v[128:129], v[226:227]
	v_mov_b64_e32 v[130:131], v[228:229]
	s_and_b64 vcc, exec, s[10:11]
	v_mov_b64_e32 v[132:133], v[230:231]
	v_mov_b64_e32 v[134:135], v[232:233]
.LBB0_408:
	v_lshlrev_b32_e32 v154, 16, v132
	v_and_b32_e32 v132, 0xffff0000, v132
	v_rcp_f32_e32 v132, v132
	v_lshlrev_b32_e32 v155, 16, v128
	v_and_b32_e32 v128, 0xffff0000, v128
	v_rcp_f32_e32 v154, v154
	v_mul_f32_e32 v132, v132, v128
	v_cndmask_b32_e64 v128, v132, v128, s[6:7]
	v_lshlrev_b32_e32 v132, 16, v133
	v_and_b32_e32 v133, 0xffff0000, v133
	v_rcp_f32_e32 v133, v133
	v_mul_f32_e32 v154, v154, v155
	v_cndmask_b32_e64 v154, v154, v155, s[6:7]
	v_lshlrev_b32_e32 v155, 16, v129
	v_and_b32_e32 v129, 0xffff0000, v129
	v_rcp_f32_e32 v132, v132
	v_mul_f32_e32 v133, v133, v129
	v_cndmask_b32_e64 v129, v133, v129, s[6:7]
	v_lshlrev_b32_e32 v133, 16, v134
	v_and_b32_e32 v134, 0xffff0000, v134
	v_rcp_f32_e32 v134, v134
	v_mul_f32_e32 v132, v132, v155
	v_cndmask_b32_e64 v132, v132, v155, s[6:7]
	v_lshlrev_b32_e32 v155, 16, v130
	v_and_b32_e32 v130, 0xffff0000, v130
	v_rcp_f32_e32 v133, v133
	v_mul_f32_e32 v134, v134, v130
	v_cndmask_b32_e64 v130, v134, v130, s[6:7]
	v_lshlrev_b32_e32 v134, 16, v135
	v_and_b32_e32 v135, 0xffff0000, v135
	v_rcp_f32_e32 v134, v134
	v_rcp_f32_e32 v135, v135
	v_lshlrev_b64 v[144:145], 11, v[142:143]
	s_mov_b64 s[22:23], 0x50000
	v_mul_f32_e32 v133, v133, v155
	v_lshl_add_u64 v[144:145], v[144:145], 0, s[22:23]
	v_cndmask_b32_e64 v133, v133, v155, s[6:7]
	v_lshlrev_b32_e32 v155, 16, v131
	v_and_b32_e32 v131, 0xffff0000, v131
	v_readlane_b32 s22, v253, 61
	v_mul_f32_e32 v134, v134, v155
	v_mul_f32_e32 v135, v135, v131
	v_readlane_b32 s23, v253, 62
	v_cndmask_b32_e64 v134, v134, v155, s[6:7]
	v_cndmask_b32_e64 v131, v135, v131, s[6:7]
	v_mul_f32_e32 v101, v101, v128
	v_mul_f32_e32 v103, v103, v129
	v_lshl_add_u64 v[128:129], s[22:23], 0, v[144:145]
	v_mul_f32_e32 v100, v100, v154
	v_mul_f32_e32 v102, v102, v132
	v_mul_f32_e32 v96, v96, v133
	v_mul_f32_e32 v97, v97, v130
	v_mul_f32_e32 v98, v98, v134
	v_mul_f32_e32 v99, v99, v131
	s_and_b64 vcc, exec, s[8:9]
	v_lshl_add_u64 v[144:145], v[140:141], 1, v[128:129]
	s_cbranch_vccnz .LBB0_410
	v_cvt_pk_bf16_f32 v128, v100, v101
	v_cvt_pk_bf16_f32 v129, v102, v103
	v_cvt_pk_bf16_f32 v130, v96, v97
	v_cvt_pk_bf16_f32 v131, v98, v99
	global_store_dwordx4 v[144:145], v[128:131], off
.LBB0_410:
	s_nop 1
	v_add_co_u32_e32 v128, vcc, 0x1a000, v138
	s_nop 1
	v_addc_co_u32_e32 v129, vcc, 0, v139, vcc
	s_waitcnt vmcnt(4)
	v_mov_b64_e32 v[128:129], v[234:235]
	v_mov_b64_e32 v[130:131], v[236:237]
	s_and_b64 vcc, exec, s[10:11]
	v_mov_b64_e32 v[132:133], v[238:239]
	v_mov_b64_e32 v[134:135], v[240:241]
; __device__ __forceinline__ unsigned cvt_pk_bf16(float lo, float hi) { unsigned r; asm("v_cvt_pk_bf16_f32 %0, %1, %2" : "=v"(r) : "v"(lo), "v"(hi)); return r; }
; __device__ __forceinline__ float bf_lo(unsigned w) { return __uint_as_float(w << 16); }
; __device__ __forceinline__ float bf_hi(unsigned w) { return __uint_as_float(w & 0xffff0000u); }
;     __device__ __forceinline__ void operator()(f32x4 (&acc)[2][2][4][2], const Unit& u, int wr, int wc, int fr, int fq) const {
;     ...
;         for (int ai = 0; ai < 2; ++ai)
; #pragma unroll
;             for (int m = 0; m < 4; ++m) { const size_t row = (size_t)(row0 + ai * HALF + m * 16);
; #pragma unroll
;                 for (int bj = 0; bj < 2; ++bj) { const size_t so = (size_t)((ai * 4 + m) * 2 + bj) * 512;
;                     const u32x4 zn = gn[so]; u32x4 zd = zn; if (!fin) zd = gd[so];
;                     float f[8];
; #pragma unroll
;                     for (int q = 0; q < 4; ++q) { f[2 * q] = fin ? bf_lo(zn[q]) : bf_lo(zn[q]) * __builtin_amdgcn_rcpf(bf_lo(zd[q])); f[2 * q + 1] = fin ? bf_hi(zn[q]) : bf_hi(zn[q]) * __builtin_amdgcn_rcpf(bf_hi(zd[q])); }
;                     f32x4 v0 = acc[ai][bj][m][0], v1 = acc[ai][bj][m][1];
;                     v0[0] *= f[0]; v0[1] *= f[1]; v0[2] *= f[2]; v0[3] *= f[3]; v1[0] *= f[4]; v1[1] *= f[5]; v1[2] *= f[6]; v1[3] *= f[7];
;                     acc[ai][bj][m][0] = v0; acc[ai][bj][m][1] = v1;
;                     if (fin) { u32x4 w; w.x = cvt_pk_bf16(v0[0], v0[1]); w.y = cvt_pk_bf16(v0[2], v0[3]); w.z = cvt_pk_bf16(v1[0], v1[1]); w.w = cvt_pk_bf16(v1[2], v1[3]);
;                         *(u32x4*)(O + row * DM + col0 + bj * HALF) = w; } }
;                 if (m & 1) { asm volatile("" ::: "memory"); __builtin_amdgcn_sched_barrier(0); } }
.LBB0_412:
	v_lshlrev_b32_e32 v154, 16, v132
	v_and_b32_e32 v132, 0xffff0000, v132
	v_rcp_f32_e32 v132, v132
	v_lshlrev_b32_e32 v155, 16, v128
	v_and_b32_e32 v128, 0xffff0000, v128
	v_rcp_f32_e32 v154, v154
	v_mul_f32_e32 v132, v132, v128
	v_cndmask_b32_e64 v128, v132, v128, s[6:7]
	v_lshlrev_b32_e32 v132, 16, v133
	v_and_b32_e32 v133, 0xffff0000, v133
	v_rcp_f32_e32 v133, v133
	v_mul_f32_e32 v154, v154, v155
	v_cndmask_b32_e64 v154, v154, v155, s[6:7]
	v_lshlrev_b32_e32 v155, 16, v129
	v_and_b32_e32 v129, 0xffff0000, v129
	v_rcp_f32_e32 v132, v132
	v_mul_f32_e32 v133, v133, v129
	v_cndmask_b32_e64 v129, v133, v129, s[6:7]
	v_lshlrev_b32_e32 v133, 16, v134
	v_and_b32_e32 v134, 0xffff0000, v134
	v_rcp_f32_e32 v134, v134
	v_mul_f32_e32 v132, v132, v155
	v_cndmask_b32_e64 v132, v132, v155, s[6:7]
	v_lshlrev_b32_e32 v155, 16, v130
	v_and_b32_e32 v130, 0xffff0000, v130
	v_rcp_f32_e32 v133, v133
	v_mul_f32_e32 v134, v134, v130
	v_cndmask_b32_e64 v130, v134, v130, s[6:7]
	v_lshlrev_b32_e32 v134, 16, v135
	v_and_b32_e32 v135, 0xffff0000, v135
	v_rcp_f32_e32 v134, v134
	v_rcp_f32_e32 v135, v135
	v_mul_f32_e32 v133, v133, v155
	v_cndmask_b32_e64 v133, v133, v155, s[6:7]
	v_lshlrev_b32_e32 v155, 16, v131
	v_and_b32_e32 v131, 0xffff0000, v131
	v_mul_f32_e32 v134, v134, v155
	v_mul_f32_e32 v135, v135, v131
	v_cndmask_b32_e64 v134, v134, v155, s[6:7]
	v_cndmask_b32_e64 v131, v135, v131, s[6:7]
	v_mul_f32_e32 v108, v108, v154
	v_mul_f32_e32 v109, v109, v128
	v_mul_f32_e32 v110, v110, v132
	v_mul_f32_e32 v111, v111, v129
	v_mul_f32_e32 v104, v104, v133
	v_mul_f32_e32 v105, v105, v130
	v_mul_f32_e32 v106, v106, v134
	s_and_b64 vcc, exec, s[8:9]
	v_mul_f32_e32 v107, v107, v131
	s_cbranch_vccnz .LBB0_414
	v_cvt_pk_bf16_f32 v128, v108, v109
	v_cvt_pk_bf16_f32 v129, v110, v111
	v_cvt_pk_bf16_f32 v130, v104, v105
	v_cvt_pk_bf16_f32 v131, v106, v107
	global_store_dwordx4 v[144:145], v[128:131], off offset:256
.LBB0_414:
	s_nop 1
	v_add_co_u32_e32 v128, vcc, 0x1c000, v138
	s_nop 1
	v_addc_co_u32_e32 v129, vcc, 0, v139, vcc
	s_waitcnt vmcnt(2)
	v_mov_b64_e32 v[128:129], v[242:243]
	v_mov_b64_e32 v[130:131], v[244:245]
	s_and_b64 vcc, exec, s[10:11]
	v_mov_b64_e32 v[132:133], v[246:247]
	v_mov_b64_e32 v[134:135], v[248:249]
.LBB0_416:
	v_lshlrev_b32_e32 v144, 16, v132
	v_and_b32_e32 v132, 0xffff0000, v132
	v_rcp_f32_e32 v132, v132
	v_lshlrev_b32_e32 v145, 16, v128
	v_and_b32_e32 v128, 0xffff0000, v128
	v_rcp_f32_e32 v144, v144
	v_mul_f32_e32 v132, v132, v128
	v_cndmask_b32_e64 v128, v132, v128, s[6:7]
	v_lshlrev_b32_e32 v132, 16, v133
	v_and_b32_e32 v133, 0xffff0000, v133
	v_rcp_f32_e32 v133, v133
	v_mul_f32_e32 v144, v144, v145
	v_cndmask_b32_e64 v144, v144, v145, s[6:7]
	v_lshlrev_b32_e32 v145, 16, v129
	v_and_b32_e32 v129, 0xffff0000, v129
	v_rcp_f32_e32 v132, v132
	v_mul_f32_e32 v133, v133, v129
	v_cndmask_b32_e64 v129, v133, v129, s[6:7]
	v_lshlrev_b32_e32 v133, 16, v134
	v_and_b32_e32 v134, 0xffff0000, v134
	v_rcp_f32_e32 v134, v134
	v_mul_f32_e32 v132, v132, v145
	v_cndmask_b32_e64 v132, v132, v145, s[6:7]
	v_lshlrev_b32_e32 v145, 16, v130
	v_and_b32_e32 v130, 0xffff0000, v130
	v_rcp_f32_e32 v133, v133
	v_mul_f32_e32 v134, v134, v130
	v_cndmask_b32_e64 v130, v134, v130, s[6:7]
	v_lshlrev_b32_e32 v134, 16, v135
	v_and_b32_e32 v135, 0xffff0000, v135
	v_rcp_f32_e32 v134, v134
	v_rcp_f32_e32 v135, v135
	v_lshlrev_b64 v[142:143], 11, v[142:143]
	s_mov_b64 s[22:23], 0x58000
	v_mul_f32_e32 v133, v133, v145
	v_lshl_add_u64 v[142:143], v[142:143], 0, s[22:23]
	v_cndmask_b32_e64 v133, v133, v145, s[6:7]
	v_lshlrev_b32_e32 v145, 16, v131
	v_and_b32_e32 v131, 0xffff0000, v131
	v_readlane_b32 s22, v253, 61
	v_mul_f32_e32 v134, v134, v145
	v_mul_f32_e32 v135, v135, v131
	v_readlane_b32 s23, v253, 62
	v_cndmask_b32_e64 v134, v134, v145, s[6:7]
	v_cndmask_b32_e64 v131, v135, v131, s[6:7]
	v_mul_f32_e32 v121, v121, v128
	v_mul_f32_e32 v123, v123, v129
	v_lshl_add_u64 v[128:129], s[22:23], 0, v[142:143]
	v_mul_f32_e32 v120, v120, v144
	v_mul_f32_e32 v122, v122, v132
	v_mul_f32_e32 v116, v116, v133
	v_mul_f32_e32 v117, v117, v130
	v_mul_f32_e32 v118, v118, v134
	v_mul_f32_e32 v119, v119, v131
	s_and_b64 vcc, exec, s[8:9]
	v_lshl_add_u64 v[140:141], v[140:141], 1, v[128:129]
	s_cbranch_vccnz .LBB0_418
	v_cvt_pk_bf16_f32 v128, v120, v121
	v_cvt_pk_bf16_f32 v129, v122, v123
	v_cvt_pk_bf16_f32 v130, v116, v117
	v_cvt_pk_bf16_f32 v131, v118, v119
	global_store_dwordx4 v[140:141], v[128:131], off
.LBB0_418:
	s_nop 1
	v_add_co_u32_e32 v128, vcc, 0x1e000, v138
	s_nop 1
	v_addc_co_u32_e32 v129, vcc, 0, v139, vcc
	s_waitcnt vmcnt(0)
	v_mov_b64_e32 v[128:129], v[202:203]
	v_mov_b64_e32 v[130:131], v[204:205]
	s_and_b64 vcc, exec, s[10:11]
	v_mov_b64_e32 v[132:133], v[194:195]
	v_mov_b64_e32 v[134:135], v[196:197]
.LBB0_420:
	v_lshlrev_b32_e32 v138, 16, v132
	v_and_b32_e32 v132, 0xffff0000, v132
	v_rcp_f32_e32 v132, v132
	v_lshlrev_b32_e32 v139, 16, v128
	v_and_b32_e32 v128, 0xffff0000, v128
	v_rcp_f32_e32 v138, v138
	v_mul_f32_e32 v132, v132, v128
	v_cndmask_b32_e64 v128, v132, v128, s[6:7]
	v_lshlrev_b32_e32 v132, 16, v133
	v_and_b32_e32 v133, 0xffff0000, v133
	v_rcp_f32_e32 v133, v133
	v_mul_f32_e32 v138, v138, v139
	v_cndmask_b32_e64 v138, v138, v139, s[6:7]
	v_lshlrev_b32_e32 v139, 16, v129
	v_and_b32_e32 v129, 0xffff0000, v129
	v_rcp_f32_e32 v132, v132
	v_mul_f32_e32 v133, v133, v129
	v_cndmask_b32_e64 v129, v133, v129, s[6:7]
	v_lshlrev_b32_e32 v133, 16, v134
	v_and_b32_e32 v134, 0xffff0000, v134
	v_rcp_f32_e32 v134, v134
	v_mul_f32_e32 v132, v132, v139
	v_cndmask_b32_e64 v132, v132, v139, s[6:7]
	v_lshlrev_b32_e32 v139, 16, v130
	v_and_b32_e32 v130, 0xffff0000, v130
	v_rcp_f32_e32 v133, v133
	v_mul_f32_e32 v134, v134, v130
	v_cndmask_b32_e64 v130, v134, v130, s[6:7]
	v_lshlrev_b32_e32 v134, 16, v135
	v_and_b32_e32 v135, 0xffff0000, v135
	v_rcp_f32_e32 v134, v134
	v_rcp_f32_e32 v135, v135
	v_mul_f32_e32 v133, v133, v139
	v_cndmask_b32_e64 v133, v133, v139, s[6:7]
	v_lshlrev_b32_e32 v139, 16, v131
	v_and_b32_e32 v131, 0xffff0000, v131
	v_mul_f32_e32 v134, v134, v139
	v_mul_f32_e32 v135, v135, v131
	v_cndmask_b32_e64 v134, v134, v139, s[6:7]
	v_cndmask_b32_e64 v131, v135, v131, s[6:7]
	v_mul_f32_e32 v124, v124, v138
	v_mul_f32_e32 v125, v125, v128
	v_mul_f32_e32 v126, v126, v132
	v_mul_f32_e32 v127, v127, v129
	v_mul_f32_e32 v112, v112, v133
	v_mul_f32_e32 v113, v113, v130
	v_mul_f32_e32 v114, v114, v134
	s_and_b64 vcc, exec, s[8:9]
	v_mul_f32_e32 v115, v115, v131
	s_cbranch_vccnz .LBB0_422
	v_cvt_pk_bf16_f32 v128, v124, v125
	v_cvt_pk_bf16_f32 v129, v126, v127
	v_cvt_pk_bf16_f32 v130, v112, v113
	v_cvt_pk_bf16_f32 v131, v114, v115
	global_store_dwordx4 v[140:141], v[128:131], off offset:256

; __device__ void conv_naive(const Params& p, int l, const bf16_t* proj, bf16_t* ycat) {
;     ...
;         u32x2 hh[10], cc[10], bb[8];
; #pragma unroll
;         for (int j = 0; j < 10; ++j) { const int ts = tb + j - 1; const bool ok = ts >= 0 && ts < SEQ; const int tc = ok ? ts : tb;
;             hh[j] = *(const u32x2*)(proj + (size_t)tc * NP + CH + c); cc[j] = *(const u32x2*)(proj + (size_t)tc * NP + CC + c);
;             if (!ok) { hh[j].x = 0u; hh[j].y = 0u; } }
; #pragma unroll
;         for (int j = 0; j < 8; ++j) bb[j] = *(const u32x2*)(proj + (size_t)(tb + j) * NP + CB + c);
.LBB0_482:
	v_ashrrev_i32_e32 v52, 4, v54
	v_and_b32_e32 v0, -8, v52
	v_add_u32_e32 v1, -1, v0
	v_cmp_gt_u32_e64 s[4:5], s22, v1
	v_and_b32_e32 v53, 0x1fc, v55
	v_mov_b64_e32 v[14:15], s[94:95]
	v_cndmask_b32_e64 v1, v0, v1, s[4:5]
	v_mad_i64_i32 v[2:3], s[12:13], v1, s63, v[14:15]
	v_lshlrev_b32_e32 v188, 1, v53
	v_lshl_add_u64 v[2:3], v[2:3], 0, v[188:189]
	v_add_co_u32_e32 v4, vcc, 0x1000, v2
	v_or_b32_e32 v10, 2, v0
	s_nop 0
	v_addc_co_u32_e32 v5, vcc, 0, v3, vcc
	global_load_dwordx2 v[120:121], v[4:5], off offset:3584
	v_add_co_u32_e32 v2, vcc, 0x2000, v2
	v_or_b32_e32 v8, 3, v0
	s_nop 0
	v_addc_co_u32_e32 v3, vcc, 0, v3, vcc
	global_load_dwordx2 v[24:25], v[2:3], off offset:1536
	v_mad_i64_i32 v[2:3], s[12:13], v0, s63, v[14:15]
	v_lshl_add_u64 v[2:3], v[2:3], 0, v[188:189]
	v_or_b32_e32 v6, 4, v0
	v_or_b32_e32 v28, 1, v0
	v_ashrrev_i32_e32 v1, 31, v0
	v_ashrrev_i32_e32 v29, 31, v28
	v_ashrrev_i32_e32 v11, 31, v10
	v_ashrrev_i32_e32 v9, 31, v8
	v_ashrrev_i32_e32 v7, 31, v6
	v_add_u32_e32 v54, s18, v54
	v_add_u32_e32 v55, s19, v55
	v_cndmask_b32_e64 v140, 0, 1, s[4:5]
	v_add_co_u32_e32 v4, vcc, s66, v2
	s_nop 0
	v_addc_co_u32_e32 v5, vcc, 0, v3, vcc
	global_load_dwordx2 v[122:123], v[4:5], off offset:3584
	v_cmp_gt_u32_e64 s[4:5], s22, v52
	v_add_co_u32_e32 v12, vcc, s92, v2
	s_nop 0
	v_cndmask_b32_e64 v2, 0, 1, s[4:5]
	v_cndmask_b32_e64 v141, 0, 1, s[4:5]
	v_or_b32_e32 v2, v0, v2
	v_addc_co_u32_e32 v13, vcc, 0, v3, vcc
	v_mad_i64_i32 v[2:3], s[12:13], v2, s63, v[14:15]
	v_lshl_add_u64 v[2:3], v[2:3], 0, v[188:189]
	global_load_dwordx2 v[30:31], v[12:13], off offset:1536
	global_load_dwordx2 v[44:45], v[12:13], off offset:512
	v_add_co_u32_e32 v4, vcc, s66, v2
	s_nop 0
	v_addc_co_u32_e32 v5, vcc, 0, v3, vcc
	global_load_dwordx2 v[124:125], v[4:5], off offset:3584
	v_add_co_u32_e32 v2, vcc, s92, v2
	s_nop 0
	v_addc_co_u32_e32 v3, vcc, 0, v3, vcc
	global_load_dwordx2 v[32:33], v[2:3], off offset:1536
	v_cndmask_b32_e64 v2, v0, v10, s[4:5]
	v_mad_i64_i32 v[2:3], s[12:13], v2, s63, v[14:15]
	v_lshl_add_u64 v[2:3], v[2:3], 0, v[188:189]
	v_add_co_u32_e32 v4, vcc, s66, v2
	s_nop 0
	v_addc_co_u32_e32 v5, vcc, 0, v3, vcc
	global_load_dwordx2 v[126:127], v[4:5], off offset:3584
	v_add_co_u32_e32 v2, vcc, s92, v2
	s_nop 1
	v_addc_co_u32_e32 v3, vcc, 0, v3, vcc
	global_load_dwordx2 v[34:35], v[2:3], off offset:1536
	v_cndmask_b32_e64 v2, v0, v8, s[4:5]
	v_mad_i64_i32 v[2:3], s[12:13], v2, s63, v[14:15]
	v_lshl_add_u64 v[2:3], v[2:3], 0, v[188:189]
	v_add_co_u32_e32 v4, vcc, s66, v2
	s_nop 0
	v_addc_co_u32_e32 v5, vcc, 0, v3, vcc
	global_load_dwordx2 v[128:129], v[4:5], off offset:3584
	v_add_co_u32_e32 v2, vcc, s92, v2
	s_nop 1
	v_addc_co_u32_e32 v3, vcc, 0, v3, vcc
	global_load_dwordx2 v[38:39], v[2:3], off offset:1536
	v_cndmask_b32_e64 v2, v0, v6, s[4:5]
	v_mad_i64_i32 v[2:3], s[12:13], v2, s63, v[14:15]
	v_lshl_add_u64 v[2:3], v[2:3], 0, v[188:189]
	v_add_co_u32_e32 v4, vcc, s66, v2
	s_nop 0
	v_addc_co_u32_e32 v5, vcc, 0, v3, vcc
	global_load_dwordx2 v[130:131], v[4:5], off offset:3584
	v_add_co_u32_e32 v2, vcc, s92, v2
	s_nop 1
	v_addc_co_u32_e32 v3, vcc, 0, v3, vcc
	global_load_dwordx2 v[40:41], v[2:3], off offset:1536
	v_or_b32_e32 v4, 5, v0
	v_cndmask_b32_e64 v2, v0, v4, s[4:5]
	v_mad_i64_i32 v[2:3], s[12:13], v2, s63, v[14:15]
	v_lshl_add_u64 v[2:3], v[2:3], 0, v[188:189]
	v_add_co_u32_e32 v16, vcc, s66, v2
	s_nop 0
	v_addc_co_u32_e32 v17, vcc, 0, v3, vcc
	global_load_dwordx2 v[132:133], v[16:17], off offset:3584
	v_add_co_u32_e32 v2, vcc, s92, v2
	v_ashrrev_i32_e32 v5, 31, v4
	s_nop 0
	v_addc_co_u32_e32 v3, vcc, 0, v3, vcc
	global_load_dwordx2 v[42:43], v[2:3], off offset:1536
	v_or_b32_e32 v2, 6, v0
	v_cndmask_b32_e64 v3, v0, v2, s[4:5]
	v_mad_i64_i32 v[16:17], s[12:13], v3, s63, v[14:15]
	v_lshl_add_u64 v[16:17], v[16:17], 0, v[188:189]
	v_add_co_u32_e32 v18, vcc, s66, v16
	v_cndmask_b32_e64 v3, 0, 7, s[4:5]
	s_nop 0
	v_addc_co_u32_e32 v19, vcc, 0, v17, vcc
	global_load_dwordx2 v[134:135], v[18:19], off offset:3584
	v_add_co_u32_e32 v16, vcc, s92, v16
	v_or_b32_e32 v3, v3, v0
	s_nop 0
	v_addc_co_u32_e32 v17, vcc, 0, v17, vcc
	global_load_dwordx2 v[46:47], v[16:17], off offset:1536
	v_mad_i64_i32 v[16:17], s[12:13], v3, s63, v[14:15]
	v_lshl_add_u64 v[16:17], v[16:17], 0, v[188:189]
	v_add_u32_e32 v3, 8, v0
	v_add_co_u32_e32 v18, vcc, s66, v16
	s_nop 0
	v_addc_co_u32_e32 v19, vcc, 0, v17, vcc
	global_load_dwordx2 v[136:137], v[18:19], off offset:3584
	v_add_co_u32_e32 v16, vcc, s92, v16
	s_nop 1
	v_addc_co_u32_e32 v17, vcc, 0, v17, vcc
	global_load_dwordx2 v[48:49], v[16:17], off offset:1536
	v_cmp_gt_u32_e64 s[4:5], s22, v3
	s_nop 1
	v_cndmask_b32_e64 v3, v0, v3, s[4:5]
	v_cndmask_b32_e64 v142, 0, 1, s[4:5]
	v_mad_i64_i32 v[16:17], s[12:13], v3, s63, v[14:15]
	v_lshl_add_u64 v[16:17], v[16:17], 0, v[188:189]
	v_add_co_u32_e32 v18, vcc, s66, v16
	v_lshlrev_b64 v[0:1], 10, v[0:1]
	s_nop 0
	v_addc_co_u32_e32 v19, vcc, 0, v17, vcc
	global_load_dwordx2 v[138:139], v[18:19], off offset:3584
	v_add_co_u32_e32 v16, vcc, s92, v16
	v_ashrrev_i32_e32 v3, 31, v2
	s_nop 0
	v_addc_co_u32_e32 v17, vcc, 0, v17, vcc
	global_load_dwordx2 v[50:51], v[16:17], off offset:1536
	v_mad_i64_i32 v[12:13], s[4:5], v28, s63, v[14:15]
	v_lshl_add_u64 v[12:13], v[12:13], 0, v[188:189]
	v_add_co_u32_e32 v12, vcc, s92, v12
	s_nop 1
	v_addc_co_u32_e32 v13, vcc, 0, v13, vcc
	global_load_dwordx2 v[36:37], v[12:13], off offset:512
	v_mad_i64_i32 v[12:13], s[4:5], v10, s63, v[14:15]
	v_lshl_add_u64 v[12:13], v[12:13], 0, v[188:189]
	v_add_co_u32_e32 v12, vcc, s92, v12
	s_nop 1
	v_addc_co_u32_e32 v13, vcc, 0, v13, vcc
	global_load_dwordx2 v[26:27], v[12:13], off offset:512
; __device__ __forceinline__ float bf_lo(unsigned w) { return __uint_as_float(w << 16); }
; __device__ __forceinline__ float bf_hi(unsigned w) { return __uint_as_float(w & 0xffff0000u); }
; __device__ void conv_naive(const Params& p, int l, const bf16_t* proj, bf16_t* ycat) {
;     ...
;         u32x2 hh[10], cc[10], bb[8];
; #pragma unroll
;         for (int j = 0; j < 10; ++j) { const int ts = tb + j - 1; const bool ok = ts >= 0 && ts < SEQ; const int tc = ok ? ts : tb;
;             hh[j] = *(const u32x2*)(proj + (size_t)tc * NP + CH + c); cc[j] = *(const u32x2*)(proj + (size_t)tc * NP + CC + c);
;             if (!ok) { hh[j].x = 0u; hh[j].y = 0u; } }
; #pragma unroll
;         for (int j = 0; j < 8; ++j) bb[j] = *(const u32x2*)(proj + (size_t)(tb + j) * NP + CB + c);
;         f32x4 w[3];
; #pragma unroll
;         for (int j = 0; j < 3; ++j) w[j] = *(const f32x4*)(p.conv_w + ((size_t)l * 3 + j) * 512 + c);
;         f32x4 u[10];
; #pragma unroll
;         for (int j = 0; j < 10; ++j) { u[j][0] = bf_lo(hh[j].x) * bf_lo(cc[j].x); u[j][1] = bf_hi(hh[j].x) * bf_hi(cc[j].x); u[j][2] = bf_lo(hh[j].y) * bf_lo(cc[j].y); u[j][3] = bf_hi(hh[j].y) * bf_hi(cc[j].y); }
; #pragma unroll
;         for (int j = 0; j < 8; ++j) { const f32x4 a = w[0] * u[j] + w[1] * u[j + 1] + w[2] * u[j + 2];
	v_mad_i64_i32 v[12:13], s[4:5], v8, s63, v[14:15]
	v_lshl_add_u64 v[12:13], v[12:13], 0, v[188:189]
	v_add_co_u32_e32 v12, vcc, s92, v12
	s_nop 1
	v_addc_co_u32_e32 v13, vcc, 0, v13, vcc
	global_load_dwordx2 v[22:23], v[12:13], off offset:512
	v_mad_i64_i32 v[12:13], s[4:5], v6, s63, v[14:15]
	v_lshl_add_u64 v[12:13], v[12:13], 0, v[188:189]
	v_add_co_u32_e32 v12, vcc, s92, v12
	s_nop 1
	v_addc_co_u32_e32 v13, vcc, 0, v13, vcc
	global_load_dwordx2 v[20:21], v[12:13], off offset:512
	v_mad_i64_i32 v[12:13], s[4:5], v4, s63, v[14:15]
	v_lshl_add_u64 v[12:13], v[12:13], 0, v[188:189]
	v_add_co_u32_e32 v12, vcc, s92, v12
	s_nop 1
	v_addc_co_u32_e32 v13, vcc, 0, v13, vcc
	global_load_dwordx2 v[18:19], v[12:13], off offset:512
	v_mad_i64_i32 v[12:13], s[4:5], v2, s63, v[14:15]
	v_lshl_add_u64 v[12:13], v[12:13], 0, v[188:189]
	v_add_co_u32_e32 v12, vcc, s92, v12
	s_nop 1
	v_addc_co_u32_e32 v13, vcc, 0, v13, vcc
	global_load_dwordx2 v[16:17], v[12:13], off offset:512
	v_or_b32_e32 v12, 7, v52
	v_mad_i64_i32 v[14:15], s[4:5], v12, s63, v[14:15]
	v_lshl_add_u64 v[14:15], v[14:15], 0, v[188:189]
	v_add_co_u32_e32 v14, vcc, s92, v14
	v_lshlrev_b32_e32 v52, 2, v53
	v_mov_b32_e32 v53, v189
	v_addc_co_u32_e32 v15, vcc, 0, v15, vcc
	v_lshl_add_u64 v[84:85], s[8:9], 0, v[52:53]
	global_load_dwordx2 v[14:15], v[14:15], off offset:512
	s_nop 0
	global_load_dwordx4 v[76:79], v52, s[8:9]
	global_load_dwordx4 v[80:83], v52, s[8:9] offset:2048
	v_add_co_u32_e32 v52, vcc, s66, v84
	v_ashrrev_i32_e32 v13, 31, v12
	s_nop 0
	v_addc_co_u32_e32 v53, vcc, 0, v85, vcc
	global_load_dwordx4 v[84:87], v[52:53], off
	s_waitcnt vmcnt(10)
	v_cmp_ne_u32_e32 vcc, 0, v142
	s_nop 1
	v_cndmask_b32_e32 v73, 0, v139, vcc
	v_cndmask_b32_e32 v75, 0, v138, vcc
	v_cmp_ne_u32_e32 vcc, 0, v140
	s_nop 1
	v_cndmask_b32_e32 v58, 0, v120, vcc
	v_cndmask_b32_e32 v56, 0, v121, vcc
	v_cmp_ne_u32_e32 vcc, 0, v141
	s_nop 1
	v_cndmask_b32_e32 v60, 0, v122, vcc
	v_cndmask_b32_e32 v57, 0, v123, vcc
	v_cndmask_b32_e32 v62, 0, v124, vcc
	v_cndmask_b32_e32 v59, 0, v125, vcc
	v_cndmask_b32_e32 v64, 0, v126, vcc
	v_cndmask_b32_e32 v61, 0, v127, vcc
	v_cndmask_b32_e32 v66, 0, v128, vcc
	v_cndmask_b32_e32 v63, 0, v129, vcc
	v_cndmask_b32_e32 v68, 0, v130, vcc
	v_cndmask_b32_e32 v65, 0, v131, vcc
	v_cndmask_b32_e32 v67, 0, v133, vcc
	v_cndmask_b32_e32 v70, 0, v132, vcc
	v_cndmask_b32_e32 v72, 0, v134, vcc
	v_cndmask_b32_e32 v69, 0, v135, vcc
	v_cndmask_b32_e32 v71, 0, v137, vcc
	v_cndmask_b32_e32 v74, 0, v136, vcc
	v_lshlrev_b32_e32 v88, 16, v24
	v_and_b32_e32 v89, 0xffff0000, v24
	v_lshlrev_b32_e32 v24, 16, v25
	v_and_b32_e32 v25, 0xffff0000, v25
	v_lshlrev_b32_e32 v90, 16, v30
	v_and_b32_e32 v91, 0xffff0000, v30
	v_lshlrev_b32_e32 v30, 16, v31
	v_and_b32_e32 v31, 0xffff0000, v31
	v_lshlrev_b32_e32 v52, 16, v58
	v_and_b32_e32 v53, 0xffff0000, v58
	v_pk_mul_f32 v[52:53], v[88:89], v[52:53]
	v_lshlrev_b32_e32 v88, 16, v56
	v_and_b32_e32 v89, 0xffff0000, v56
	v_pk_mul_f32 v[24:25], v[24:25], v[88:89]
	v_lshlrev_b32_e32 v88, 16, v60
	v_and_b32_e32 v89, 0xffff0000, v60
	v_lshlrev_b32_e32 v56, 16, v57
	v_and_b32_e32 v57, 0xffff0000, v57
	v_pk_mul_f32 v[88:89], v[88:89], v[90:91]
	v_pk_mul_f32 v[30:31], v[56:57], v[30:31]
	v_lshlrev_b32_e32 v56, 16, v62
	v_and_b32_e32 v57, 0xffff0000, v62
	v_lshlrev_b32_e32 v90, 16, v32
	v_and_b32_e32 v91, 0xffff0000, v32
	v_lshlrev_b32_e32 v58, 16, v59
	v_and_b32_e32 v59, 0xffff0000, v59
	v_lshlrev_b32_e32 v32, 16, v33
	v_and_b32_e32 v33, 0xffff0000, v33
	v_pk_mul_f32 v[56:57], v[56:57], v[90:91]
	v_pk_mul_f32 v[32:33], v[58:59], v[32:33]
	v_lshlrev_b32_e32 v58, 16, v64
	v_and_b32_e32 v59, 0xffff0000, v64
	v_lshlrev_b32_e32 v90, 16, v34
	v_and_b32_e32 v91, 0xffff0000, v34
	v_lshlrev_b32_e32 v60, 16, v61
	v_and_b32_e32 v61, 0xffff0000, v61
	v_lshlrev_b32_e32 v34, 16, v35
	v_and_b32_e32 v35, 0xffff0000, v35
	v_pk_mul_f32 v[58:59], v[58:59], v[90:91]
	v_pk_mul_f32 v[34:35], v[60:61], v[34:35]
	v_lshlrev_b32_e32 v60, 16, v66
	v_and_b32_e32 v61, 0xffff0000, v66
	v_lshlrev_b32_e32 v90, 16, v38
	v_and_b32_e32 v91, 0xffff0000, v38
	v_lshlrev_b32_e32 v62, 16, v63
	v_and_b32_e32 v63, 0xffff0000, v63
	v_lshlrev_b32_e32 v38, 16, v39
	v_and_b32_e32 v39, 0xffff0000, v39
	v_pk_mul_f32 v[60:61], v[60:61], v[90:91]
	v_pk_mul_f32 v[38:39], v[62:63], v[38:39]
	v_lshlrev_b32_e32 v62, 16, v68
	v_and_b32_e32 v63, 0xffff0000, v68
	v_lshlrev_b32_e32 v90, 16, v40
	v_and_b32_e32 v91, 0xffff0000, v40
	v_lshlrev_b32_e32 v64, 16, v65
	v_and_b32_e32 v65, 0xffff0000, v65
	v_lshlrev_b32_e32 v40, 16, v41
	v_and_b32_e32 v41, 0xffff0000, v41
	v_pk_mul_f32 v[62:63], v[62:63], v[90:91]
	v_pk_mul_f32 v[40:41], v[64:65], v[40:41]
	v_lshlrev_b32_e32 v64, 16, v70
	v_and_b32_e32 v65, 0xffff0000, v70
	v_lshlrev_b32_e32 v90, 16, v42
	v_and_b32_e32 v91, 0xffff0000, v42
	v_lshlrev_b32_e32 v66, 16, v67
	v_and_b32_e32 v67, 0xffff0000, v67
	v_lshlrev_b32_e32 v42, 16, v43
	v_and_b32_e32 v43, 0xffff0000, v43
	v_pk_mul_f32 v[64:65], v[64:65], v[90:91]
	v_pk_mul_f32 v[42:43], v[66:67], v[42:43]
	v_lshlrev_b32_e32 v66, 16, v72
	v_and_b32_e32 v67, 0xffff0000, v72
	v_lshlrev_b32_e32 v90, 16, v46
	v_and_b32_e32 v91, 0xffff0000, v46
	v_lshlrev_b32_e32 v68, 16, v69
	v_and_b32_e32 v69, 0xffff0000, v69
	v_lshlrev_b32_e32 v46, 16, v47
	v_and_b32_e32 v47, 0xffff0000, v47
	v_pk_mul_f32 v[66:67], v[66:67], v[90:91]
	v_pk_mul_f32 v[46:47], v[68:69], v[46:47]
	v_lshlrev_b32_e32 v68, 16, v74
	v_and_b32_e32 v69, 0xffff0000, v74
	v_lshlrev_b32_e32 v90, 16, v48
	v_and_b32_e32 v91, 0xffff0000, v48
	v_lshlrev_b32_e32 v70, 16, v71
	v_and_b32_e32 v71, 0xffff0000, v71
	v_lshlrev_b32_e32 v48, 16, v49
	v_and_b32_e32 v49, 0xffff0000, v49
	v_pk_mul_f32 v[68:69], v[68:69], v[90:91]
	v_pk_mul_f32 v[48:49], v[70:71], v[48:49]
	v_lshlrev_b32_e32 v70, 16, v75
	v_and_b32_e32 v71, 0xffff0000, v75
	v_lshlrev_b32_e32 v74, 16, v50
	v_and_b32_e32 v75, 0xffff0000, v50
	s_waitcnt vmcnt(0)
; __device__ __forceinline__ unsigned cvt_pk_bf16(float lo, float hi) { unsigned r; asm("v_cvt_pk_bf16_f32 %0, %1, %2" : "=v"(r) : "v"(lo), "v"(hi)); return r; }
; __device__ __forceinline__ float bf_lo(unsigned w) { return __uint_as_float(w << 16); }
; __device__ __forceinline__ float bf_hi(unsigned w) { return __uint_as_float(w & 0xffff0000u); }
; __device__ void conv_naive(const Params& p, int l, const bf16_t* proj, bf16_t* ycat) {
;     ...
;         for (int j = 0; j < 10; ++j) { u[j][0] = bf_lo(hh[j].x) * bf_lo(cc[j].x); u[j][1] = bf_hi(hh[j].x) * bf_hi(cc[j].x); u[j][2] = bf_lo(hh[j].y) * bf_lo(cc[j].y); u[j][3] = bf_hi(hh[j].y) * bf_hi(cc[j].y); }
; #pragma unroll
;         for (int j = 0; j < 8; ++j) { const f32x4 a = w[0] * u[j] + w[1] * u[j + 1] + w[2] * u[j + 2];
;             u32x2 o; o.x = cvt_pk_bf16(a[0] * bf_lo(bb[j].x), a[1] * bf_hi(bb[j].x)); o.y = cvt_pk_bf16(a[2] * bf_lo(bb[j].y), a[3] * bf_hi(bb[j].y));
;             *(u32x2*)(ycat + (size_t)SEQ * 512 + (size_t)(tb + j) * 512 + c) = o; }
;     }
	v_pk_mul_f32 v[90:91], v[88:89], v[80:81]
	v_pk_mul_f32 v[70:71], v[70:71], v[74:75]
	v_pk_mul_f32 v[74:75], v[30:31], v[82:83]
	v_pk_fma_f32 v[52:53], v[52:53], v[76:77], v[90:91]
	v_pk_fma_f32 v[24:25], v[24:25], v[78:79], v[74:75]
	v_pk_fma_f32 v[52:53], v[56:57], v[84:85], v[52:53]
	v_lshlrev_b32_e32 v74, 16, v44
	v_and_b32_e32 v44, 0xffff0000, v44
	v_mul_f32_e32 v52, v52, v74
	v_mul_f32_e32 v44, v53, v44
	v_lshlrev_b32_e32 v72, 16, v73
	v_and_b32_e32 v73, 0xffff0000, v73
	v_lshlrev_b32_e32 v50, 16, v51
	v_and_b32_e32 v51, 0xffff0000, v51
	v_pk_fma_f32 v[24:25], v[32:33], v[86:87], v[24:25]
	v_cvt_pk_bf16_f32 v44, v52, v44
	v_lshlrev_b32_e32 v52, 16, v45
	v_and_b32_e32 v45, 0xffff0000, v45
	v_pk_mul_f32 v[50:51], v[72:73], v[50:51]
	v_lshl_add_u64 v[72:73], s[20:21], 0, v[188:189]
	v_mul_f32_e32 v24, v24, v52
	v_mul_f32_e32 v25, v25, v45
	v_cvt_pk_bf16_f32 v45, v24, v25
	v_lshl_add_u64 v[0:1], v[72:73], 0, v[0:1]
	v_pk_mul_f32 v[24:25], v[56:57], v[80:81]
	global_store_dwordx2 v[0:1], v[44:45], off
	v_pk_mul_f32 v[0:1], v[32:33], v[82:83]
	v_pk_fma_f32 v[24:25], v[88:89], v[76:77], v[24:25]
	v_pk_fma_f32 v[0:1], v[30:31], v[78:79], v[0:1]
	v_pk_fma_f32 v[24:25], v[58:59], v[84:85], v[24:25]
	v_lshlrev_b32_e32 v30, 16, v36
	v_mul_f32_e32 v24, v24, v30
	v_and_b32_e32 v30, 0xffff0000, v36
	v_mul_f32_e32 v25, v25, v30
	v_pk_fma_f32 v[0:1], v[34:35], v[86:87], v[0:1]
	v_cvt_pk_bf16_f32 v24, v24, v25
	v_lshlrev_b32_e32 v25, 16, v37
	v_mul_f32_e32 v0, v0, v25
	v_and_b32_e32 v25, 0xffff0000, v37
	v_mul_f32_e32 v1, v1, v25
	v_cvt_pk_bf16_f32 v25, v0, v1
	v_lshlrev_b64 v[0:1], 10, v[28:29]
	v_lshl_add_u64 v[0:1], v[72:73], 0, v[0:1]
	global_store_dwordx2 v[0:1], v[24:25], off
	v_pk_mul_f32 v[24:25], v[58:59], v[80:81]
	v_pk_mul_f32 v[0:1], v[34:35], v[82:83]
	v_pk_fma_f32 v[24:25], v[56:57], v[76:77], v[24:25]
	v_lshlrev_b32_e32 v28, 16, v26
	v_pk_fma_f32 v[24:25], v[60:61], v[84:85], v[24:25]
	v_and_b32_e32 v26, 0xffff0000, v26
	v_pk_fma_f32 v[0:1], v[32:33], v[78:79], v[0:1]
	v_mul_f32_e32 v24, v24, v28
	v_mul_f32_e32 v25, v25, v26
	v_pk_fma_f32 v[0:1], v[38:39], v[86:87], v[0:1]
	v_cvt_pk_bf16_f32 v24, v24, v25
	v_lshlrev_b32_e32 v25, 16, v27
	v_mul_f32_e32 v0, v0, v25
	v_and_b32_e32 v25, 0xffff0000, v27
	v_mul_f32_e32 v1, v1, v25
	v_cvt_pk_bf16_f32 v25, v0, v1
	v_lshlrev_b64 v[0:1], 10, v[10:11]
	v_pk_mul_f32 v[10:11], v[60:61], v[80:81]
	v_lshl_add_u64 v[0:1], v[72:73], 0, v[0:1]
	v_pk_fma_f32 v[10:11], v[58:59], v[76:77], v[10:11]
	global_store_dwordx2 v[0:1], v[24:25], off
	v_pk_mul_f32 v[0:1], v[38:39], v[82:83]
	v_pk_fma_f32 v[10:11], v[62:63], v[84:85], v[10:11]
	v_lshlrev_b32_e32 v24, 16, v22
	v_and_b32_e32 v22, 0xffff0000, v22
	v_pk_fma_f32 v[0:1], v[34:35], v[78:79], v[0:1]
	v_mul_f32_e32 v10, v10, v24
	v_mul_f32_e32 v11, v11, v22
	v_pk_fma_f32 v[0:1], v[40:41], v[86:87], v[0:1]
	v_cvt_pk_bf16_f32 v10, v10, v11
	v_lshlrev_b32_e32 v11, 16, v23
	v_mul_f32_e32 v0, v0, v11
	v_and_b32_e32 v11, 0xffff0000, v23
	v_mul_f32_e32 v1, v1, v11
	v_cvt_pk_bf16_f32 v11, v0, v1
	v_lshlrev_b64 v[0:1], 10, v[8:9]
	v_pk_mul_f32 v[8:9], v[62:63], v[80:81]
	v_lshl_add_u64 v[0:1], v[72:73], 0, v[0:1]
	v_pk_fma_f32 v[8:9], v[60:61], v[76:77], v[8:9]
	global_store_dwordx2 v[0:1], v[10:11], off
	v_pk_fma_f32 v[8:9], v[64:65], v[84:85], v[8:9]
	v_lshlrev_b32_e32 v10, 16, v20
	v_pk_mul_f32 v[0:1], v[40:41], v[82:83]
	v_mul_f32_e32 v8, v8, v10
	v_and_b32_e32 v10, 0xffff0000, v20
	v_pk_fma_f32 v[0:1], v[38:39], v[78:79], v[0:1]
	v_mul_f32_e32 v9, v9, v10
	v_pk_fma_f32 v[0:1], v[42:43], v[86:87], v[0:1]
	v_cvt_pk_bf16_f32 v8, v8, v9
	v_lshlrev_b32_e32 v9, 16, v21
	v_mul_f32_e32 v0, v0, v9
	v_and_b32_e32 v9, 0xffff0000, v21
	v_mul_f32_e32 v1, v1, v9
	v_cvt_pk_bf16_f32 v9, v0, v1
	v_lshlrev_b64 v[0:1], 10, v[6:7]
	v_pk_mul_f32 v[6:7], v[64:65], v[80:81]
	v_lshl_add_u64 v[0:1], v[72:73], 0, v[0:1]
	v_pk_fma_f32 v[6:7], v[62:63], v[76:77], v[6:7]
	global_store_dwordx2 v[0:1], v[8:9], off
	v_pk_fma_f32 v[6:7], v[66:67], v[84:85], v[6:7]
	v_lshlrev_b32_e32 v8, 16, v18
	v_pk_mul_f32 v[0:1], v[42:43], v[82:83]
	v_mul_f32_e32 v6, v6, v8
	v_and_b32_e32 v8, 0xffff0000, v18
	v_pk_fma_f32 v[0:1], v[40:41], v[78:79], v[0:1]
	v_mul_f32_e32 v7, v7, v8
	v_pk_fma_f32 v[0:1], v[46:47], v[86:87], v[0:1]
	v_cvt_pk_bf16_f32 v6, v6, v7
	v_lshlrev_b32_e32 v7, 16, v19
	v_mul_f32_e32 v0, v0, v7
	v_and_b32_e32 v7, 0xffff0000, v19
	v_mul_f32_e32 v1, v1, v7
	v_cvt_pk_bf16_f32 v7, v0, v1
	v_lshlrev_b64 v[0:1], 10, v[4:5]
	v_pk_mul_f32 v[4:5], v[66:67], v[80:81]
	v_lshl_add_u64 v[0:1], v[72:73], 0, v[0:1]
	v_pk_fma_f32 v[4:5], v[64:65], v[76:77], v[4:5]
	global_store_dwordx2 v[0:1], v[6:7], off
	v_pk_fma_f32 v[4:5], v[68:69], v[84:85], v[4:5]
	v_lshlrev_b32_e32 v6, 16, v16
	v_pk_mul_f32 v[0:1], v[46:47], v[82:83]
	v_mul_f32_e32 v4, v4, v6
	v_and_b32_e32 v6, 0xffff0000, v16
	v_pk_fma_f32 v[0:1], v[42:43], v[78:79], v[0:1]
	v_mul_f32_e32 v5, v5, v6
	v_pk_fma_f32 v[0:1], v[48:49], v[86:87], v[0:1]
	v_cvt_pk_bf16_f32 v4, v4, v5
	v_lshlrev_b32_e32 v5, 16, v17
	v_mul_f32_e32 v0, v0, v5
	v_and_b32_e32 v5, 0xffff0000, v17
	v_mul_f32_e32 v1, v1, v5
	v_cvt_pk_bf16_f32 v5, v0, v1
	v_lshlrev_b64 v[0:1], 10, v[2:3]
	v_pk_mul_f32 v[2:3], v[68:69], v[80:81]
	v_lshl_add_u64 v[0:1], v[72:73], 0, v[0:1]
	v_pk_fma_f32 v[2:3], v[66:67], v[76:77], v[2:3]
	global_store_dwordx2 v[0:1], v[4:5], off
	v_pk_fma_f32 v[2:3], v[70:71], v[84:85], v[2:3]
	v_lshlrev_b32_e32 v4, 16, v14
	v_pk_mul_f32 v[0:1], v[48:49], v[82:83]
	v_mul_f32_e32 v2, v2, v4
	v_and_b32_e32 v4, 0xffff0000, v14
	v_pk_fma_f32 v[0:1], v[46:47], v[78:79], v[0:1]
	v_mul_f32_e32 v3, v3, v4
	v_pk_fma_f32 v[0:1], v[50:51], v[86:87], v[0:1]
	v_cvt_pk_bf16_f32 v2, v2, v3
	v_lshlrev_b32_e32 v3, 16, v15
	v_mul_f32_e32 v0, v0, v3
	v_and_b32_e32 v3, 0xffff0000, v15
	v_mul_f32_e32 v1, v1, v3
	s_mov_b32 s4, 0x3ffff
	v_cvt_pk_bf16_f32 v3, v0, v1
	v_lshlrev_b64 v[0:1], 10, v[12:13]
	v_cmp_lt_i32_e32 vcc, s4, v54
	v_lshl_add_u64 v[0:1], v[72:73], 0, v[0:1]
	s_or_b64 s[10:11], vcc, s[10:11]
	global_store_dwordx2 v[0:1], v[2:3], off
	s_andn2_b64 exec, exec, s[10:11]
	s_cbranch_execnz .LBB0_482
